# LN split-chunk assembly: residual + 8 partial loads back to back, counted waits, entry drain removed (mutually exclusive with the plain-chunk load)
# speedup vs baseline: 1.0032x; 1.0032x over previous
; __device__ __forceinline__ void ln_load_row(const Params& p, const float* src, int which, int r, int lane, f32x4 (&x)[8]) {
;   const float* part = (const float*)(p.ws + WS_PART);
;   const float* s = src + (size_t)r * 2048;
;   const float* rs = which == 0 ? (r < TOKP ? p.in[0] + (size_t)r * 2048 : p.in[1] + (size_t)(r - TOKP) * 2048) : (const float*)(p.ws + WS_X1) + (size_t)r * 2048;
;   const int pm = r >> 8, gid = pm >> 3, fm = gid * 8, gsz = (36 - fm) < 8 ? (36 - fm) : 8;
; #pragma unroll
;   for (int k = 0; k < 8; ++k) {
;     const int wg = gid * 64 + k * gsz + (pm - fm), off = wg % 36, xcd = wg / 36;
;     if (off >= 32) {
;       const int j = (off - 32) * 8 + xcd;
;       f32x4 v = *(const f32x4*)(rs + 256 * k + 4 * lane) * ALPHA;
;       const float* pp = part + (size_t)j * 8 * 65536 + (r & 255) * 256 + 4 * lane;
;       f32x4 t[8];
; #pragma unroll
;       for (int q = 0; q < 8; ++q) t[q] = *(const f32x4*)(pp + (size_t)q * 65536);
; #pragma unroll
;       for (int q = 0; q < 8; ++q) v += t[q];
;       x[k] = v;
.LBB0_94:
	s_or_saveexec_b64 s[36:37], s[36:37]
	v_add_u32_e32 v64, 0xffffe000, v66
	v_lshlrev_b64 v[36:37], 13, v[64:65]
	v_lshl_add_u64 v[36:37], s[6:7], 0, v[36:37]
	v_cndmask_b32_e32 v37, v37, v101, vcc
	v_cndmask_b32_e32 v36, v36, v100, vcc
	v_lshlrev_b32_e32 v64, 2, v68
	v_lshl_add_u64 v[114:115], v[36:37], 0, v[64:65]
	v_and_b32_e32 v36, 0xff00, v129
	v_lshlrev_b32_e32 v36, 2, v36
	v_mov_b32_e32 v37, v65
	v_lshl_add_u64 v[116:117], v[92:93], 0, v[36:37]
	s_xor_b64 exec, exec, s[36:37]
	s_cbranch_execz .LBB0_96
	v_lshlrev_b32_e32 v24, 3, v35
	s_movk_i32 s29, 0xff00
	v_add3_u32 v34, v34, v24, s29
	v_ashrrev_i32_e32 v35, 31, v34
	v_lshlrev_b64 v[34:35], 21, v[34:35]
	v_lshl_add_u64 v[38:39], v[116:117], 0, v[34:35]
	v_add_co_u32_e32 v44, vcc, 0x40000, v38
	global_load_dwordx4 v[24:27], v[114:115], off
	s_nop 0
	v_addc_co_u32_e32 v45, vcc, 0, v39, vcc
	v_add_co_u32_e32 v48, vcc, 0x80000, v38
	global_load_dwordx4 v[34:37], v[38:39], off
	s_nop 0
	global_load_dwordx4 v[44:47], v[44:45], off
	v_addc_co_u32_e32 v49, vcc, 0, v39, vcc
	v_add_co_u32_e32 v52, vcc, 0xc0000, v38
	s_nop 1
	v_addc_co_u32_e32 v53, vcc, 0, v39, vcc
	v_add_co_u32_e32 v56, vcc, 0x100000, v38
	global_load_dwordx4 v[48:51], v[48:49], off
	s_nop 0
	global_load_dwordx4 v[52:55], v[52:53], off
	v_addc_co_u32_e32 v57, vcc, 0, v39, vcc
	v_add_co_u32_e32 v60, vcc, 0x140000, v38
	s_nop 0
	s_nop 1
	v_addc_co_u32_e32 v61, vcc, 0, v39, vcc
	v_add_co_u32_e32 v118, vcc, 0x180000, v38
	global_load_dwordx4 v[56:59], v[56:57], off
	s_nop 0
	global_load_dwordx4 v[60:63], v[60:61], off
	v_addc_co_u32_e32 v119, vcc, 0, v39, vcc
	v_add_co_u32_e32 v38, vcc, 0x1c0000, v38
	global_load_dwordx4 v[118:121], v[118:119], off
	s_nop 0
	v_addc_co_u32_e32 v39, vcc, 0, v39, vcc
	global_load_dwordx4 v[130:133], v[38:39], off
	s_waitcnt vmcnt(7)
	v_pk_fma_f32 v[26:27], v[26:27], s[2:3], v[36:37] op_sel_hi:[1,0,1]
	v_pk_fma_f32 v[24:25], v[24:25], s[2:3], v[34:35] op_sel_hi:[1,0,1]
	s_waitcnt vmcnt(6)
	v_pk_add_f32 v[26:27], v[26:27], v[46:47]
	v_pk_add_f32 v[24:25], v[24:25], v[44:45]
	s_waitcnt vmcnt(5)
	v_pk_add_f32 v[26:27], v[26:27], v[50:51]
	v_pk_add_f32 v[24:25], v[24:25], v[48:49]
	s_waitcnt vmcnt(4)
	v_pk_add_f32 v[26:27], v[26:27], v[54:55]
	v_pk_add_f32 v[24:25], v[24:25], v[52:53]
	s_waitcnt vmcnt(3)
	v_pk_add_f32 v[26:27], v[26:27], v[58:59]
	v_pk_add_f32 v[24:25], v[24:25], v[56:57]
	s_waitcnt vmcnt(2)
	v_pk_add_f32 v[26:27], v[26:27], v[62:63]
	v_pk_add_f32 v[24:25], v[24:25], v[60:61]
	s_waitcnt vmcnt(1)
	v_pk_add_f32 v[26:27], v[26:27], v[120:121]
	v_pk_add_f32 v[24:25], v[24:25], v[118:119]
	s_waitcnt vmcnt(0)
	v_pk_add_f32 v[26:27], v[26:27], v[132:133]
	v_pk_add_f32 v[24:25], v[24:25], v[130:131]

; __device__ __forceinline__ void ln_load_row(const Params& p, const float* src, int which, int r, int lane, f32x4 (&x)[8]) {
;     ...
;     const int wg = gid * 64 + k * gsz + (pm - fm), off = wg % 36, xcd = wg / 36;
;     if (off >= 32) {
;       const int j = (off - 32) * 8 + xcd;
;       f32x4 v = *(const f32x4*)(rs + 256 * k + 4 * lane) * ALPHA;
;       const float* pp = part + (size_t)j * 8 * 65536 + (r & 255) * 256 + 4 * lane;
;       f32x4 t[8];
; #pragma unroll
;       for (int q = 0; q < 8; ++q) t[q] = *(const f32x4*)(pp + (size_t)q * 65536);
; #pragma unroll
;       for (int q = 0; q < 8; ++q) v += t[q];
;       x[k] = v;
.LBB0_98:
	s_andn2_saveexec_b64 s[36:37], s[36:37]
	s_cbranch_execz .LBB0_100
	v_lshlrev_b32_e32 v32, 3, v38
	s_movk_i32 s29, 0xff00
	v_add3_u32 v38, v37, v32, s29
	v_ashrrev_i32_e32 v39, 31, v38
	v_lshlrev_b64 v[38:39], 21, v[38:39]
	v_lshl_add_u64 v[38:39], v[116:117], 0, v[38:39]
	v_add_co_u32_e32 v48, vcc, 0x40000, v38
	global_load_dwordx4 v[32:35], v[114:115], off offset:1024
	s_nop 0
	v_addc_co_u32_e32 v49, vcc, 0, v39, vcc
	v_add_co_u32_e32 v52, vcc, 0x80000, v38
	global_load_dwordx4 v[44:47], v[38:39], off
	s_nop 0
	global_load_dwordx4 v[48:51], v[48:49], off
	v_addc_co_u32_e32 v53, vcc, 0, v39, vcc
	v_add_co_u32_e32 v56, vcc, 0xc0000, v38
	s_nop 1
	v_addc_co_u32_e32 v57, vcc, 0, v39, vcc
	v_add_co_u32_e32 v62, vcc, 0x100000, v38
	global_load_dwordx4 v[52:55], v[52:53], off
	s_nop 0
	global_load_dwordx4 v[56:59], v[56:57], off
	v_addc_co_u32_e32 v63, vcc, 0, v39, vcc
	v_add_co_u32_e32 v122, vcc, 0x140000, v38
	s_nop 0
	s_nop 1
	v_addc_co_u32_e32 v123, vcc, 0, v39, vcc
	global_load_dwordx4 v[118:121], v[62:63], off
	global_load_dwordx4 v[130:133], v[122:123], off
	v_add_co_u32_e32 v62, vcc, 0x180000, v38
	s_nop 1
	v_addc_co_u32_e32 v63, vcc, 0, v39, vcc
	v_add_co_u32_e32 v38, vcc, 0x1c0000, v38
	global_load_dwordx4 v[134:137], v[62:63], off
	s_nop 0
	v_addc_co_u32_e32 v39, vcc, 0, v39, vcc
	global_load_dwordx4 v[138:141], v[38:39], off
	s_waitcnt vmcnt(7)
	v_pk_fma_f32 v[34:35], v[34:35], s[2:3], v[46:47] op_sel_hi:[1,0,1]
	v_pk_fma_f32 v[32:33], v[32:33], s[2:3], v[44:45] op_sel_hi:[1,0,1]
	s_waitcnt vmcnt(6)
	v_pk_add_f32 v[34:35], v[34:35], v[50:51]
	v_pk_add_f32 v[32:33], v[32:33], v[48:49]
	s_waitcnt vmcnt(5)
	v_pk_add_f32 v[34:35], v[34:35], v[54:55]
	v_pk_add_f32 v[32:33], v[32:33], v[52:53]
	s_waitcnt vmcnt(4)
	v_pk_add_f32 v[34:35], v[34:35], v[58:59]
	v_pk_add_f32 v[32:33], v[32:33], v[56:57]
	s_waitcnt vmcnt(3)
	v_pk_add_f32 v[34:35], v[34:35], v[120:121]
	v_pk_add_f32 v[32:33], v[32:33], v[118:119]
	s_waitcnt vmcnt(2)
	v_pk_add_f32 v[34:35], v[34:35], v[132:133]
	v_pk_add_f32 v[32:33], v[32:33], v[130:131]
	s_waitcnt vmcnt(1)
	v_pk_add_f32 v[34:35], v[34:35], v[136:137]
	v_pk_add_f32 v[32:33], v[32:33], v[134:135]
	s_waitcnt vmcnt(0)
	v_pk_add_f32 v[34:35], v[34:35], v[140:141]
	v_pk_add_f32 v[32:33], v[32:33], v[138:139]

; __device__ __forceinline__ void ln_load_row(const Params& p, const float* src, int which, int r, int lane, f32x4 (&x)[8]) {
;     ...
;     const int wg = gid * 64 + k * gsz + (pm - fm), off = wg % 36, xcd = wg / 36;
;     if (off >= 32) {
;       const int j = (off - 32) * 8 + xcd;
;       f32x4 v = *(const f32x4*)(rs + 256 * k + 4 * lane) * ALPHA;
;       const float* pp = part + (size_t)j * 8 * 65536 + (r & 255) * 256 + 4 * lane;
;       f32x4 t[8];
; #pragma unroll
;       for (int q = 0; q < 8; ++q) t[q] = *(const f32x4*)(pp + (size_t)q * 65536);
; #pragma unroll
;       for (int q = 0; q < 8; ++q) v += t[q];
;       x[k] = v;
.LBB0_102:
	s_andn2_saveexec_b64 s[36:37], s[36:37]
	s_cbranch_execz .LBB0_104
	v_lshlrev_b32_e32 v36, 3, v46
	s_movk_i32 s29, 0xff00
	v_add3_u32 v46, v45, v36, s29
	v_ashrrev_i32_e32 v47, 31, v46
	v_lshlrev_b64 v[46:47], 21, v[46:47]
	v_lshl_add_u64 v[58:59], v[116:117], 0, v[46:47]
	v_add_co_u32_e32 v50, vcc, 0x40000, v58
	global_load_dwordx4 v[36:39], v[114:115], off offset:2048
	s_nop 0
	v_addc_co_u32_e32 v51, vcc, 0, v59, vcc
	v_add_co_u32_e32 v54, vcc, 0x80000, v58
	global_load_dwordx4 v[46:49], v[58:59], off
	s_nop 0
	global_load_dwordx4 v[50:53], v[50:51], off
	v_addc_co_u32_e32 v55, vcc, 0, v59, vcc
	v_add_co_u32_e32 v62, vcc, 0xc0000, v58
	s_nop 1
	v_addc_co_u32_e32 v63, vcc, 0, v59, vcc
	global_load_dwordx4 v[54:57], v[54:55], off
	s_nop 0
	global_load_dwordx4 v[118:121], v[62:63], off
	v_add_co_u32_e32 v62, vcc, 0x100000, v58
	s_nop 0
	s_nop 1
	v_addc_co_u32_e32 v63, vcc, 0, v59, vcc
	v_add_co_u32_e32 v122, vcc, 0x140000, v58
	s_nop 1
	v_addc_co_u32_e32 v123, vcc, 0, v59, vcc
	global_load_dwordx4 v[130:133], v[62:63], off
	global_load_dwordx4 v[134:137], v[122:123], off
	v_add_co_u32_e32 v62, vcc, 0x180000, v58
	s_nop 0
	s_nop 1
	v_addc_co_u32_e32 v63, vcc, 0, v59, vcc
	v_add_co_u32_e32 v58, vcc, 0x1c0000, v58
	global_load_dwordx4 v[138:141], v[62:63], off
	s_nop 0
	v_addc_co_u32_e32 v59, vcc, 0, v59, vcc
	global_load_dwordx4 v[142:145], v[58:59], off
	s_waitcnt vmcnt(7)
	v_pk_fma_f32 v[38:39], v[38:39], s[2:3], v[48:49] op_sel_hi:[1,0,1]
	v_pk_fma_f32 v[36:37], v[36:37], s[2:3], v[46:47] op_sel_hi:[1,0,1]
	s_waitcnt vmcnt(6)
	v_pk_add_f32 v[38:39], v[38:39], v[52:53]
	v_pk_add_f32 v[36:37], v[36:37], v[50:51]
	s_waitcnt vmcnt(5)
	v_pk_add_f32 v[38:39], v[38:39], v[56:57]
	v_pk_add_f32 v[36:37], v[36:37], v[54:55]
	s_waitcnt vmcnt(4)
	v_pk_add_f32 v[38:39], v[38:39], v[120:121]
	v_pk_add_f32 v[36:37], v[36:37], v[118:119]
	s_waitcnt vmcnt(3)
	v_pk_add_f32 v[38:39], v[38:39], v[132:133]
	v_pk_add_f32 v[36:37], v[36:37], v[130:131]
	s_waitcnt vmcnt(2)
	v_pk_add_f32 v[38:39], v[38:39], v[136:137]
	v_pk_add_f32 v[36:37], v[36:37], v[134:135]
	s_waitcnt vmcnt(1)
	v_pk_add_f32 v[38:39], v[38:39], v[140:141]
	v_pk_add_f32 v[36:37], v[36:37], v[138:139]
	s_waitcnt vmcnt(0)
	v_pk_add_f32 v[38:39], v[38:39], v[144:145]
	v_pk_add_f32 v[36:37], v[36:37], v[142:143]

; __device__ __forceinline__ void ln_load_row(const Params& p, const float* src, int which, int r, int lane, f32x4 (&x)[8]) {
;     ...
;     const int wg = gid * 64 + k * gsz + (pm - fm), off = wg % 36, xcd = wg / 36;
;     if (off >= 32) {
;       const int j = (off - 32) * 8 + xcd;
;       f32x4 v = *(const f32x4*)(rs + 256 * k + 4 * lane) * ALPHA;
;       const float* pp = part + (size_t)j * 8 * 65536 + (r & 255) * 256 + 4 * lane;
;       f32x4 t[8];
; #pragma unroll
;       for (int q = 0; q < 8; ++q) t[q] = *(const f32x4*)(pp + (size_t)q * 65536);
; #pragma unroll
;       for (int q = 0; q < 8; ++q) v += t[q];
;       x[k] = v;
.LBB0_106:
	s_andn2_saveexec_b64 s[36:37], s[36:37]
	s_cbranch_execz .LBB0_108
	v_lshlrev_b32_e32 v44, 3, v50
	s_movk_i32 s29, 0xff00
	v_add3_u32 v50, v49, v44, s29
	v_ashrrev_i32_e32 v51, 31, v50
	v_lshlrev_b64 v[50:51], 21, v[50:51]
	v_lshl_add_u64 v[58:59], v[116:117], 0, v[50:51]
	v_add_co_u32_e32 v54, vcc, 0x40000, v58
	global_load_dwordx4 v[44:47], v[114:115], off offset:3072
	s_nop 0
	v_addc_co_u32_e32 v55, vcc, 0, v59, vcc
	v_add_co_u32_e32 v62, vcc, 0x80000, v58
	global_load_dwordx4 v[50:53], v[58:59], off
	s_nop 0
	global_load_dwordx4 v[54:57], v[54:55], off
	v_addc_co_u32_e32 v63, vcc, 0, v59, vcc
	v_add_co_u32_e32 v122, vcc, 0xc0000, v58
	s_nop 1
	v_addc_co_u32_e32 v123, vcc, 0, v59, vcc
	global_load_dwordx4 v[118:121], v[62:63], off
	global_load_dwordx4 v[130:133], v[122:123], off
	v_add_co_u32_e32 v62, vcc, 0x100000, v58
	s_nop 0
	s_nop 1
	v_addc_co_u32_e32 v63, vcc, 0, v59, vcc
	v_add_co_u32_e32 v122, vcc, 0x140000, v58
	s_nop 1
	v_addc_co_u32_e32 v123, vcc, 0, v59, vcc
	global_load_dwordx4 v[134:137], v[62:63], off
	global_load_dwordx4 v[138:141], v[122:123], off
	v_add_co_u32_e32 v62, vcc, 0x180000, v58
	s_nop 0
	s_nop 1
	v_addc_co_u32_e32 v63, vcc, 0, v59, vcc
	v_add_co_u32_e32 v58, vcc, 0x1c0000, v58
	global_load_dwordx4 v[142:145], v[62:63], off
	s_nop 0
	v_addc_co_u32_e32 v59, vcc, 0, v59, vcc
	global_load_dwordx4 v[146:149], v[58:59], off
	s_waitcnt vmcnt(7)
	v_pk_fma_f32 v[46:47], v[46:47], s[2:3], v[52:53] op_sel_hi:[1,0,1]
	v_pk_fma_f32 v[44:45], v[44:45], s[2:3], v[50:51] op_sel_hi:[1,0,1]
	s_waitcnt vmcnt(6)
	v_pk_add_f32 v[46:47], v[46:47], v[56:57]
	v_pk_add_f32 v[44:45], v[44:45], v[54:55]
	s_waitcnt vmcnt(5)
	v_pk_add_f32 v[46:47], v[46:47], v[120:121]
	v_pk_add_f32 v[44:45], v[44:45], v[118:119]
	s_waitcnt vmcnt(4)
	v_pk_add_f32 v[46:47], v[46:47], v[132:133]
	v_pk_add_f32 v[44:45], v[44:45], v[130:131]
	s_waitcnt vmcnt(3)
	v_pk_add_f32 v[46:47], v[46:47], v[136:137]
	v_pk_add_f32 v[44:45], v[44:45], v[134:135]
	s_waitcnt vmcnt(2)
	v_pk_add_f32 v[46:47], v[46:47], v[140:141]
	v_pk_add_f32 v[44:45], v[44:45], v[138:139]
	s_waitcnt vmcnt(1)
	v_pk_add_f32 v[46:47], v[46:47], v[144:145]
	v_pk_add_f32 v[44:45], v[44:45], v[142:143]
	s_waitcnt vmcnt(0)
	v_pk_add_f32 v[46:47], v[46:47], v[148:149]
	v_pk_add_f32 v[44:45], v[44:45], v[146:147]

; __device__ __forceinline__ void ln_load_row(const Params& p, const float* src, int which, int r, int lane, f32x4 (&x)[8]) {
;     ...
;     const int wg = gid * 64 + k * gsz + (pm - fm), off = wg % 36, xcd = wg / 36;
;     if (off >= 32) {
;       const int j = (off - 32) * 8 + xcd;
;       f32x4 v = *(const f32x4*)(rs + 256 * k + 4 * lane) * ALPHA;
;       const float* pp = part + (size_t)j * 8 * 65536 + (r & 255) * 256 + 4 * lane;
;       f32x4 t[8];
; #pragma unroll
;       for (int q = 0; q < 8; ++q) t[q] = *(const f32x4*)(pp + (size_t)q * 65536);
; #pragma unroll
;       for (int q = 0; q < 8; ++q) v += t[q];
;       x[k] = v;
.LBB0_110:
	s_andn2_saveexec_b64 s[36:37], s[36:37]
	s_cbranch_execz .LBB0_112
	v_lshlrev_b32_e32 v48, 3, v54
	s_movk_i32 s29, 0xff00
	v_add3_u32 v54, v53, v48, s29
	v_ashrrev_i32_e32 v55, 31, v54
	v_add_co_u32_e32 v48, vcc, 0x1000, v114
	v_lshlrev_b64 v[54:55], 21, v[54:55]
	s_nop 0
	v_addc_co_u32_e32 v49, vcc, 0, v115, vcc
	v_lshl_add_u64 v[58:59], v[116:117], 0, v[54:55]
	v_add_co_u32_e32 v62, vcc, 0x40000, v58
	global_load_dwordx4 v[48:51], v[48:49], off
	s_nop 0
	v_addc_co_u32_e32 v63, vcc, 0, v59, vcc
	global_load_dwordx4 v[54:57], v[58:59], off
	global_load_dwordx4 v[118:121], v[62:63], off
	v_add_co_u32_e32 v62, vcc, 0x80000, v58
	s_nop 1
	v_addc_co_u32_e32 v63, vcc, 0, v59, vcc
	v_add_co_u32_e32 v122, vcc, 0xc0000, v58
	s_nop 0
	s_nop 1
	v_addc_co_u32_e32 v123, vcc, 0, v59, vcc
	global_load_dwordx4 v[130:133], v[62:63], off
	global_load_dwordx4 v[134:137], v[122:123], off
	v_add_co_u32_e32 v62, vcc, 0x100000, v58
	s_nop 1
	v_addc_co_u32_e32 v63, vcc, 0, v59, vcc
	v_add_co_u32_e32 v122, vcc, 0x140000, v58
	s_nop 0
	s_nop 1
	v_addc_co_u32_e32 v123, vcc, 0, v59, vcc
	global_load_dwordx4 v[138:141], v[62:63], off
	global_load_dwordx4 v[142:145], v[122:123], off
	v_add_co_u32_e32 v62, vcc, 0x180000, v58
	s_nop 1
	v_addc_co_u32_e32 v63, vcc, 0, v59, vcc
	v_add_co_u32_e32 v58, vcc, 0x1c0000, v58
	global_load_dwordx4 v[146:149], v[62:63], off
	s_nop 0
	v_addc_co_u32_e32 v59, vcc, 0, v59, vcc
	global_load_dwordx4 v[150:153], v[58:59], off
	s_waitcnt vmcnt(7)
	v_pk_fma_f32 v[50:51], v[50:51], s[2:3], v[56:57] op_sel_hi:[1,0,1]
	v_pk_fma_f32 v[48:49], v[48:49], s[2:3], v[54:55] op_sel_hi:[1,0,1]
	s_waitcnt vmcnt(6)
	v_pk_add_f32 v[50:51], v[50:51], v[120:121]
	v_pk_add_f32 v[48:49], v[48:49], v[118:119]
	s_waitcnt vmcnt(5)
	v_pk_add_f32 v[50:51], v[50:51], v[132:133]
	v_pk_add_f32 v[48:49], v[48:49], v[130:131]
	s_waitcnt vmcnt(4)
	v_pk_add_f32 v[50:51], v[50:51], v[136:137]
	v_pk_add_f32 v[48:49], v[48:49], v[134:135]
	s_waitcnt vmcnt(3)
	v_pk_add_f32 v[50:51], v[50:51], v[140:141]
	v_pk_add_f32 v[48:49], v[48:49], v[138:139]
	s_waitcnt vmcnt(2)
	v_pk_add_f32 v[50:51], v[50:51], v[144:145]
	v_pk_add_f32 v[48:49], v[48:49], v[142:143]
	s_waitcnt vmcnt(1)
	v_pk_add_f32 v[50:51], v[50:51], v[148:149]
	v_pk_add_f32 v[48:49], v[48:49], v[146:147]
	s_waitcnt vmcnt(0)
	v_pk_add_f32 v[50:51], v[50:51], v[152:153]
	v_pk_add_f32 v[48:49], v[48:49], v[150:151]

; __device__ __forceinline__ void ln_load_row(const Params& p, const float* src, int which, int r, int lane, f32x4 (&x)[8]) {
;     ...
;     const int wg = gid * 64 + k * gsz + (pm - fm), off = wg % 36, xcd = wg / 36;
;     if (off >= 32) {
;       const int j = (off - 32) * 8 + xcd;
;       f32x4 v = *(const f32x4*)(rs + 256 * k + 4 * lane) * ALPHA;
;       const float* pp = part + (size_t)j * 8 * 65536 + (r & 255) * 256 + 4 * lane;
;       f32x4 t[8];
; #pragma unroll
;       for (int q = 0; q < 8; ++q) t[q] = *(const f32x4*)(pp + (size_t)q * 65536);
; #pragma unroll
;       for (int q = 0; q < 8; ++q) v += t[q];
;       x[k] = v;
.LBB0_114:
	s_andn2_saveexec_b64 s[36:37], s[36:37]
	s_cbranch_execz .LBB0_116
	v_lshlrev_b32_e32 v52, 3, v58
	s_movk_i32 s29, 0xff00
	v_add3_u32 v58, v57, v52, s29
	v_ashrrev_i32_e32 v59, 31, v58
	v_add_co_u32_e32 v52, vcc, 0x1000, v114
	v_lshlrev_b64 v[58:59], 21, v[58:59]
	s_nop 0
	v_addc_co_u32_e32 v53, vcc, 0, v115, vcc
	v_lshl_add_u64 v[58:59], v[116:117], 0, v[58:59]
	v_add_co_u32_e32 v62, vcc, 0x40000, v58
	global_load_dwordx4 v[52:55], v[52:53], off offset:1024
	s_nop 0
	v_addc_co_u32_e32 v63, vcc, 0, v59, vcc
	global_load_dwordx4 v[118:121], v[58:59], off
	global_load_dwordx4 v[130:133], v[62:63], off
	v_add_co_u32_e32 v62, vcc, 0x80000, v58
	s_nop 1
	v_addc_co_u32_e32 v63, vcc, 0, v59, vcc
	v_add_co_u32_e32 v122, vcc, 0xc0000, v58
	s_nop 0
	s_nop 1
	v_addc_co_u32_e32 v123, vcc, 0, v59, vcc
	global_load_dwordx4 v[134:137], v[62:63], off
	global_load_dwordx4 v[138:141], v[122:123], off
	v_add_co_u32_e32 v62, vcc, 0x100000, v58
	s_nop 1
	v_addc_co_u32_e32 v63, vcc, 0, v59, vcc
	v_add_co_u32_e32 v122, vcc, 0x140000, v58
	s_nop 0
	s_nop 1
	v_addc_co_u32_e32 v123, vcc, 0, v59, vcc
	global_load_dwordx4 v[142:145], v[62:63], off
	global_load_dwordx4 v[146:149], v[122:123], off
	v_add_co_u32_e32 v62, vcc, 0x180000, v58
	s_nop 1
	v_addc_co_u32_e32 v63, vcc, 0, v59, vcc
	v_add_co_u32_e32 v58, vcc, 0x1c0000, v58
	global_load_dwordx4 v[150:153], v[62:63], off
	s_nop 0
	v_addc_co_u32_e32 v59, vcc, 0, v59, vcc
	global_load_dwordx4 v[154:157], v[58:59], off
	s_waitcnt vmcnt(7)
	v_pk_fma_f32 v[54:55], v[54:55], s[2:3], v[120:121] op_sel_hi:[1,0,1]
	v_pk_fma_f32 v[52:53], v[52:53], s[2:3], v[118:119] op_sel_hi:[1,0,1]
	s_waitcnt vmcnt(6)
	v_pk_add_f32 v[54:55], v[54:55], v[132:133]
	v_pk_add_f32 v[52:53], v[52:53], v[130:131]
	s_waitcnt vmcnt(5)
	v_pk_add_f32 v[54:55], v[54:55], v[136:137]
	v_pk_add_f32 v[52:53], v[52:53], v[134:135]
	s_waitcnt vmcnt(4)
	v_pk_add_f32 v[54:55], v[54:55], v[140:141]
	v_pk_add_f32 v[52:53], v[52:53], v[138:139]
	s_waitcnt vmcnt(3)
	v_pk_add_f32 v[54:55], v[54:55], v[144:145]
	v_pk_add_f32 v[52:53], v[52:53], v[142:143]
	s_waitcnt vmcnt(2)
	v_pk_add_f32 v[54:55], v[54:55], v[148:149]
	v_pk_add_f32 v[52:53], v[52:53], v[146:147]
	s_waitcnt vmcnt(1)
	v_pk_add_f32 v[54:55], v[54:55], v[152:153]
	v_pk_add_f32 v[52:53], v[52:53], v[150:151]
	s_waitcnt vmcnt(0)
	v_pk_add_f32 v[54:55], v[54:55], v[156:157]
	v_pk_add_f32 v[52:53], v[52:53], v[154:155]

; __device__ __forceinline__ void ln_load_row(const Params& p, const float* src, int which, int r, int lane, f32x4 (&x)[8]) {
;     ...
;     const int wg = gid * 64 + k * gsz + (pm - fm), off = wg % 36, xcd = wg / 36;
;     if (off >= 32) {
;       const int j = (off - 32) * 8 + xcd;
;       f32x4 v = *(const f32x4*)(rs + 256 * k + 4 * lane) * ALPHA;
;       const float* pp = part + (size_t)j * 8 * 65536 + (r & 255) * 256 + 4 * lane;
;       f32x4 t[8];
; #pragma unroll
;       for (int q = 0; q < 8; ++q) t[q] = *(const f32x4*)(pp + (size_t)q * 65536);
; #pragma unroll
;       for (int q = 0; q < 8; ++q) v += t[q];
;       x[k] = v;
.LBB0_118:
	s_andn2_saveexec_b64 s[36:37], s[36:37]
	s_cbranch_execz .LBB0_120
	v_lshlrev_b32_e32 v56, 3, v63
	s_movk_i32 s29, 0xff00
	v_add3_u32 v62, v62, v56, s29
	v_ashrrev_i32_e32 v63, 31, v62
	v_add_co_u32_e32 v56, vcc, 0x1000, v114
	v_lshlrev_b64 v[62:63], 21, v[62:63]
	s_nop 0
	v_addc_co_u32_e32 v57, vcc, 0, v115, vcc
	v_lshl_add_u64 v[62:63], v[116:117], 0, v[62:63]
	v_add_co_u32_e32 v122, vcc, 0x40000, v62
	global_load_dwordx4 v[56:59], v[56:57], off offset:2048
	s_nop 0
	v_addc_co_u32_e32 v123, vcc, 0, v63, vcc
	global_load_dwordx4 v[118:121], v[62:63], off
	global_load_dwordx4 v[130:133], v[122:123], off
	v_add_co_u32_e32 v122, vcc, 0x80000, v62
	s_nop 1
	v_addc_co_u32_e32 v123, vcc, 0, v63, vcc
	v_add_co_u32_e32 v138, vcc, 0xc0000, v62
	s_nop 0
	s_nop 1
	v_addc_co_u32_e32 v139, vcc, 0, v63, vcc
	global_load_dwordx4 v[134:137], v[122:123], off
	s_nop 0
	global_load_dwordx4 v[138:141], v[138:139], off
	v_add_co_u32_e32 v122, vcc, 0x100000, v62
	s_nop 1
	v_addc_co_u32_e32 v123, vcc, 0, v63, vcc
	v_add_co_u32_e32 v146, vcc, 0x140000, v62
	s_nop 0
	s_nop 1
	v_addc_co_u32_e32 v147, vcc, 0, v63, vcc
	global_load_dwordx4 v[142:145], v[122:123], off
	s_nop 0
	global_load_dwordx4 v[146:149], v[146:147], off
	v_add_co_u32_e32 v122, vcc, 0x180000, v62
	s_nop 1
	v_addc_co_u32_e32 v123, vcc, 0, v63, vcc
	v_add_co_u32_e32 v62, vcc, 0x1c0000, v62
	global_load_dwordx4 v[150:153], v[122:123], off
	s_nop 0
	v_addc_co_u32_e32 v63, vcc, 0, v63, vcc
	global_load_dwordx4 v[154:157], v[62:63], off
	s_waitcnt vmcnt(7)
	v_pk_fma_f32 v[58:59], v[58:59], s[2:3], v[120:121] op_sel_hi:[1,0,1]
	v_pk_fma_f32 v[56:57], v[56:57], s[2:3], v[118:119] op_sel_hi:[1,0,1]
	s_waitcnt vmcnt(6)
	v_pk_add_f32 v[58:59], v[58:59], v[132:133]
	v_pk_add_f32 v[56:57], v[56:57], v[130:131]
	s_waitcnt vmcnt(5)
	v_pk_add_f32 v[58:59], v[58:59], v[136:137]
	v_pk_add_f32 v[56:57], v[56:57], v[134:135]
	s_waitcnt vmcnt(4)
	v_pk_add_f32 v[58:59], v[58:59], v[140:141]
	v_pk_add_f32 v[56:57], v[56:57], v[138:139]
	s_waitcnt vmcnt(3)
	v_pk_add_f32 v[58:59], v[58:59], v[144:145]
	v_pk_add_f32 v[56:57], v[56:57], v[142:143]
	s_waitcnt vmcnt(2)
	v_pk_add_f32 v[58:59], v[58:59], v[148:149]
	v_pk_add_f32 v[56:57], v[56:57], v[146:147]
	s_waitcnt vmcnt(1)
	v_pk_add_f32 v[58:59], v[58:59], v[152:153]
	v_pk_add_f32 v[56:57], v[56:57], v[150:151]
	s_waitcnt vmcnt(0)
	v_pk_add_f32 v[58:59], v[58:59], v[156:157]
	v_pk_add_f32 v[56:57], v[56:57], v[154:155]

; __device__ __forceinline__ void ln_load_row(const Params& p, const float* src, int which, int r, int lane, f32x4 (&x)[8]) {
;     ...
;     const int wg = gid * 64 + k * gsz + (pm - fm), off = wg % 36, xcd = wg / 36;
;     if (off >= 32) {
;       const int j = (off - 32) * 8 + xcd;
;       f32x4 v = *(const f32x4*)(rs + 256 * k + 4 * lane) * ALPHA;
;       const float* pp = part + (size_t)j * 8 * 65536 + (r & 255) * 256 + 4 * lane;
;       f32x4 t[8];
; #pragma unroll
;       for (int q = 0; q < 8; ++q) t[q] = *(const f32x4*)(pp + (size_t)q * 65536);
; #pragma unroll
;       for (int q = 0; q < 8; ++q) v += t[q];
;       x[k] = v;
.LBB0_122:
	s_andn2_saveexec_b64 s[36:37], s[36:37]
	s_cbranch_execz .LBB0_124
	v_lshlrev_b32_e32 v60, 3, v103
	s_movk_i32 s29, 0xff00
	v_add3_u32 v118, v67, v60, s29
	v_add_co_u32_e32 v60, vcc, 0x1000, v114
	v_ashrrev_i32_e32 v119, 31, v118
	s_nop 0
	v_addc_co_u32_e32 v61, vcc, 0, v115, vcc
	v_lshlrev_b64 v[114:115], 21, v[118:119]
	v_lshl_add_u64 v[122:123], v[116:117], 0, v[114:115]
	v_add_co_u32_e32 v118, vcc, 0x40000, v122
	global_load_dwordx4 v[60:63], v[60:61], off offset:3072
	s_nop 0
	v_addc_co_u32_e32 v119, vcc, 0, v123, vcc
	v_add_co_u32_e32 v130, vcc, 0x80000, v122
	global_load_dwordx4 v[114:117], v[122:123], off
	s_nop 0
	global_load_dwordx4 v[118:121], v[118:119], off
	v_addc_co_u32_e32 v131, vcc, 0, v123, vcc
	v_add_co_u32_e32 v134, vcc, 0xc0000, v122
	s_nop 1
	v_addc_co_u32_e32 v135, vcc, 0, v123, vcc
	v_add_co_u32_e32 v138, vcc, 0x100000, v122
	global_load_dwordx4 v[130:133], v[130:131], off
	s_nop 0
	global_load_dwordx4 v[134:137], v[134:135], off
	v_addc_co_u32_e32 v139, vcc, 0, v123, vcc
	v_add_co_u32_e32 v142, vcc, 0x140000, v122
	s_nop 0
	s_nop 1
	v_addc_co_u32_e32 v143, vcc, 0, v123, vcc
	v_add_co_u32_e32 v146, vcc, 0x180000, v122
	global_load_dwordx4 v[138:141], v[138:139], off
	s_nop 0
	global_load_dwordx4 v[142:145], v[142:143], off
	v_addc_co_u32_e32 v147, vcc, 0, v123, vcc
	v_add_co_u32_e32 v122, vcc, 0x1c0000, v122
	global_load_dwordx4 v[146:149], v[146:147], off
	s_nop 0
	v_addc_co_u32_e32 v123, vcc, 0, v123, vcc
	global_load_dwordx4 v[150:153], v[122:123], off
	s_waitcnt vmcnt(7)
	v_pk_fma_f32 v[62:63], v[62:63], s[2:3], v[116:117] op_sel_hi:[1,0,1]
	v_pk_fma_f32 v[60:61], v[60:61], s[2:3], v[114:115] op_sel_hi:[1,0,1]
	s_waitcnt vmcnt(6)
	v_pk_add_f32 v[62:63], v[62:63], v[120:121]
	v_pk_add_f32 v[60:61], v[60:61], v[118:119]
	s_waitcnt vmcnt(5)
	v_pk_add_f32 v[62:63], v[62:63], v[132:133]
	v_pk_add_f32 v[60:61], v[60:61], v[130:131]
	s_waitcnt vmcnt(4)
	v_pk_add_f32 v[62:63], v[62:63], v[136:137]
	v_pk_add_f32 v[60:61], v[60:61], v[134:135]
	s_waitcnt vmcnt(3)
	v_pk_add_f32 v[62:63], v[62:63], v[140:141]
	v_pk_add_f32 v[60:61], v[60:61], v[138:139]
	s_waitcnt vmcnt(2)
	v_pk_add_f32 v[62:63], v[62:63], v[144:145]
	v_pk_add_f32 v[60:61], v[60:61], v[142:143]
	s_waitcnt vmcnt(1)
	v_pk_add_f32 v[62:63], v[62:63], v[148:149]
	v_pk_add_f32 v[60:61], v[60:61], v[146:147]
	s_waitcnt vmcnt(0)
	v_pk_add_f32 v[62:63], v[62:63], v[152:153]
	v_pk_add_f32 v[60:61], v[60:61], v[150:151]

; __device__ __forceinline__ void ln_load_row(const Params& p, const float* src, int which, int r, int lane, f32x4 (&x)[8]) {
;   const float* part = (const float*)(p.ws + WS_PART);
;   const float* s = src + (size_t)r * 2048;
;   const float* rs = which == 0 ? (r < TOKP ? p.in[0] + (size_t)r * 2048 : p.in[1] + (size_t)(r - TOKP) * 2048) : (const float*)(p.ws + WS_X1) + (size_t)r * 2048;
;   const int pm = r >> 8, gid = pm >> 3, fm = gid * 8, gsz = (36 - fm) < 8 ? (36 - fm) : 8;
; #pragma unroll
;   for (int k = 0; k < 8; ++k) {
;     const int wg = gid * 64 + k * gsz + (pm - fm), off = wg % 36, xcd = wg / 36;
;     if (off >= 32) {
;       const int j = (off - 32) * 8 + xcd;
;       f32x4 v = *(const f32x4*)(rs + 256 * k + 4 * lane) * ALPHA;
;       const float* pp = part + (size_t)j * 8 * 65536 + (r & 255) * 256 + 4 * lane;
;       f32x4 t[8];
; #pragma unroll
;       for (int q = 0; q < 8; ++q) t[q] = *(const f32x4*)(pp + (size_t)q * 65536);
; #pragma unroll
;       for (int q = 0; q < 8; ++q) v += t[q];
;       x[k] = v;
.LBB0_127:
	s_or_saveexec_b64 s[38:39], s[38:39]
	v_add_u32_e32 v10, 0xffffe000, v114
	v_mov_b32_e32 v11, v65
	v_lshlrev_b64 v[10:11], 13, v[10:11]
	v_lshl_add_u64 v[4:5], s[4:5], 0, v[4:5]
	v_lshl_add_u64 v[10:11], s[6:7], 0, v[10:11]
	v_cndmask_b32_e32 v5, v11, v5, vcc
	v_cndmask_b32_e32 v4, v10, v4, vcc
	v_readlane_b32 s29, v255, 10
	v_lshl_add_u64 v[118:119], v[4:5], 0, v[64:65]
	v_mov_b32_e32 v5, v65
	v_add_u32_e32 v4, s29, v129
	v_and_b32_e32 v4, 0xff00, v4
	v_lshlrev_b32_e32 v4, 2, v4
	v_lshl_add_u64 v[120:121], v[92:93], 0, v[4:5]
	s_xor_b64 exec, exec, s[38:39]
	s_cbranch_execz .LBB0_129
	v_lshlrev_b32_e32 v0, 3, v9
	s_movk_i32 s29, 0xff00
	v_add3_u32 v4, v8, v0, s29
	v_ashrrev_i32_e32 v5, 31, v4
	v_lshlrev_b64 v[4:5], 21, v[4:5]
	v_lshl_add_u64 v[4:5], v[120:121], 0, v[4:5]
	v_add_co_u32_e32 v12, vcc, 0x40000, v4
	global_load_dwordx4 v[0:3], v[118:119], off
	s_nop 0
	v_addc_co_u32_e32 v13, vcc, 0, v5, vcc
	v_add_co_u32_e32 v16, vcc, 0x80000, v4
	global_load_dwordx4 v[8:11], v[4:5], off
	s_nop 0
	global_load_dwordx4 v[12:15], v[12:13], off
	v_addc_co_u32_e32 v17, vcc, 0, v5, vcc
	v_add_co_u32_e32 v20, vcc, 0xc0000, v4
	s_nop 1
	v_addc_co_u32_e32 v21, vcc, 0, v5, vcc
	v_add_co_u32_e32 v28, vcc, 0x100000, v4
	global_load_dwordx4 v[16:19], v[16:17], off
	s_nop 0
	global_load_dwordx4 v[20:23], v[20:21], off
	v_addc_co_u32_e32 v29, vcc, 0, v5, vcc
	v_add_co_u32_e32 v40, vcc, 0x140000, v4
	s_nop 0
	s_nop 1
	v_addc_co_u32_e32 v41, vcc, 0, v5, vcc
	v_add_co_u32_e32 v122, vcc, 0x180000, v4
	global_load_dwordx4 v[28:31], v[28:29], off
	s_nop 0
	global_load_dwordx4 v[40:43], v[40:41], off
	v_addc_co_u32_e32 v123, vcc, 0, v5, vcc
	v_add_co_u32_e32 v4, vcc, 0x1c0000, v4
	global_load_dwordx4 v[130:133], v[122:123], off
	s_nop 0
	v_addc_co_u32_e32 v5, vcc, 0, v5, vcc
	global_load_dwordx4 v[134:137], v[4:5], off
	s_waitcnt vmcnt(7)
	v_pk_fma_f32 v[2:3], v[2:3], s[2:3], v[10:11] op_sel_hi:[1,0,1]
	v_pk_fma_f32 v[0:1], v[0:1], s[2:3], v[8:9] op_sel_hi:[1,0,1]
	s_waitcnt vmcnt(6)
	v_pk_add_f32 v[2:3], v[2:3], v[14:15]
	v_pk_add_f32 v[0:1], v[0:1], v[12:13]
	s_waitcnt vmcnt(5)
	v_pk_add_f32 v[2:3], v[2:3], v[18:19]
	v_pk_add_f32 v[0:1], v[0:1], v[16:17]
	s_waitcnt vmcnt(4)
	v_pk_add_f32 v[2:3], v[2:3], v[22:23]
	v_pk_add_f32 v[0:1], v[0:1], v[20:21]
	s_waitcnt vmcnt(3)
	v_pk_add_f32 v[2:3], v[2:3], v[30:31]
	v_pk_add_f32 v[0:1], v[0:1], v[28:29]
	s_waitcnt vmcnt(2)
	v_pk_add_f32 v[2:3], v[2:3], v[42:43]
	v_pk_add_f32 v[0:1], v[0:1], v[40:41]
	s_waitcnt vmcnt(1)
	v_pk_add_f32 v[2:3], v[2:3], v[132:133]
	v_pk_add_f32 v[0:1], v[0:1], v[130:131]
	s_waitcnt vmcnt(0)
	v_pk_add_f32 v[2:3], v[2:3], v[136:137]
	v_pk_add_f32 v[0:1], v[0:1], v[134:135]

; __device__ __forceinline__ void ln_load_row(const Params& p, const float* src, int which, int r, int lane, f32x4 (&x)[8]) {
;     ...
;     const int wg = gid * 64 + k * gsz + (pm - fm), off = wg % 36, xcd = wg / 36;
;     if (off >= 32) {
;       const int j = (off - 32) * 8 + xcd;
;       f32x4 v = *(const f32x4*)(rs + 256 * k + 4 * lane) * ALPHA;
;       const float* pp = part + (size_t)j * 8 * 65536 + (r & 255) * 256 + 4 * lane;
;       f32x4 t[8];
; #pragma unroll
;       for (int q = 0; q < 8; ++q) t[q] = *(const f32x4*)(pp + (size_t)q * 65536);
; #pragma unroll
;       for (int q = 0; q < 8; ++q) v += t[q];
;       x[k] = v;
.LBB0_131:
	s_andn2_saveexec_b64 s[38:39], s[38:39]
	s_cbranch_execz .LBB0_133
	v_lshlrev_b32_e32 v4, 3, v10
	s_movk_i32 s29, 0xff00
	v_add3_u32 v10, v9, v4, s29
	v_ashrrev_i32_e32 v11, 31, v10
	v_lshlrev_b64 v[10:11], 21, v[10:11]
	v_lshl_add_u64 v[22:23], v[120:121], 0, v[10:11]
	v_add_co_u32_e32 v14, vcc, 0x40000, v22
	global_load_dwordx4 v[4:7], v[118:119], off offset:1024
	s_nop 0
	v_addc_co_u32_e32 v15, vcc, 0, v23, vcc
	v_add_co_u32_e32 v18, vcc, 0x80000, v22
	global_load_dwordx4 v[10:13], v[22:23], off
	s_nop 0
	global_load_dwordx4 v[14:17], v[14:15], off
	v_addc_co_u32_e32 v19, vcc, 0, v23, vcc
	v_add_co_u32_e32 v28, vcc, 0xc0000, v22
	s_nop 1
	v_addc_co_u32_e32 v29, vcc, 0, v23, vcc
	v_add_co_u32_e32 v42, vcc, 0x100000, v22
	global_load_dwordx4 v[18:21], v[18:19], off
	s_nop 0
	global_load_dwordx4 v[28:31], v[28:29], off
	v_addc_co_u32_e32 v43, vcc, 0, v23, vcc
	v_add_co_u32_e32 v122, vcc, 0x140000, v22
	s_nop 0
	s_nop 1
	v_addc_co_u32_e32 v123, vcc, 0, v23, vcc
	global_load_dwordx4 v[130:133], v[42:43], off
	global_load_dwordx4 v[134:137], v[122:123], off
	v_add_co_u32_e32 v42, vcc, 0x180000, v22
	s_nop 1
	v_addc_co_u32_e32 v43, vcc, 0, v23, vcc
	v_add_co_u32_e32 v22, vcc, 0x1c0000, v22
	global_load_dwordx4 v[138:141], v[42:43], off
	s_nop 0
	v_addc_co_u32_e32 v23, vcc, 0, v23, vcc
	global_load_dwordx4 v[142:145], v[22:23], off
	s_waitcnt vmcnt(7)
	v_pk_fma_f32 v[6:7], v[6:7], s[2:3], v[12:13] op_sel_hi:[1,0,1]
	v_pk_fma_f32 v[4:5], v[4:5], s[2:3], v[10:11] op_sel_hi:[1,0,1]
	s_waitcnt vmcnt(6)
	v_pk_add_f32 v[6:7], v[6:7], v[16:17]
	v_pk_add_f32 v[4:5], v[4:5], v[14:15]
	s_waitcnt vmcnt(5)
	v_pk_add_f32 v[6:7], v[6:7], v[20:21]
	v_pk_add_f32 v[4:5], v[4:5], v[18:19]
	s_waitcnt vmcnt(4)
	v_pk_add_f32 v[6:7], v[6:7], v[30:31]
	v_pk_add_f32 v[4:5], v[4:5], v[28:29]
	s_waitcnt vmcnt(3)
	v_pk_add_f32 v[6:7], v[6:7], v[132:133]
	v_pk_add_f32 v[4:5], v[4:5], v[130:131]
	s_waitcnt vmcnt(2)
	v_pk_add_f32 v[6:7], v[6:7], v[136:137]
	v_pk_add_f32 v[4:5], v[4:5], v[134:135]
	s_waitcnt vmcnt(1)
	v_pk_add_f32 v[6:7], v[6:7], v[140:141]
	v_pk_add_f32 v[4:5], v[4:5], v[138:139]
	s_waitcnt vmcnt(0)
	v_pk_add_f32 v[6:7], v[6:7], v[144:145]
	v_pk_add_f32 v[4:5], v[4:5], v[142:143]

; __device__ __forceinline__ void ln_load_row(const Params& p, const float* src, int which, int r, int lane, f32x4 (&x)[8]) {
;     ...
;     const int wg = gid * 64 + k * gsz + (pm - fm), off = wg % 36, xcd = wg / 36;
;     if (off >= 32) {
;       const int j = (off - 32) * 8 + xcd;
;       f32x4 v = *(const f32x4*)(rs + 256 * k + 4 * lane) * ALPHA;
;       const float* pp = part + (size_t)j * 8 * 65536 + (r & 255) * 256 + 4 * lane;
;       f32x4 t[8];
; #pragma unroll
;       for (int q = 0; q < 8; ++q) t[q] = *(const f32x4*)(pp + (size_t)q * 65536);
; #pragma unroll
;       for (int q = 0; q < 8; ++q) v += t[q];
;       x[k] = v;
.LBB0_135:
	s_andn2_saveexec_b64 s[38:39], s[38:39]
	s_cbranch_execz .LBB0_137
	v_lshlrev_b32_e32 v8, 3, v14
	s_movk_i32 s29, 0xff00
	v_add3_u32 v14, v13, v8, s29
	v_ashrrev_i32_e32 v15, 31, v14
	v_lshlrev_b64 v[14:15], 21, v[14:15]
	v_lshl_add_u64 v[22:23], v[120:121], 0, v[14:15]
	v_add_co_u32_e32 v18, vcc, 0x40000, v22
	global_load_dwordx4 v[8:11], v[118:119], off offset:2048
	s_nop 0
	v_addc_co_u32_e32 v19, vcc, 0, v23, vcc
	v_add_co_u32_e32 v28, vcc, 0x80000, v22
	global_load_dwordx4 v[14:17], v[22:23], off
	s_nop 0
	global_load_dwordx4 v[18:21], v[18:19], off
	v_addc_co_u32_e32 v29, vcc, 0, v23, vcc
	v_add_co_u32_e32 v42, vcc, 0xc0000, v22
	s_nop 1
	v_addc_co_u32_e32 v43, vcc, 0, v23, vcc
	global_load_dwordx4 v[28:31], v[28:29], off
	s_nop 0
	global_load_dwordx4 v[130:133], v[42:43], off
	v_add_co_u32_e32 v42, vcc, 0x100000, v22
	s_nop 0
	s_nop 1
	v_addc_co_u32_e32 v43, vcc, 0, v23, vcc
	v_add_co_u32_e32 v122, vcc, 0x140000, v22
	s_nop 1
	v_addc_co_u32_e32 v123, vcc, 0, v23, vcc
	global_load_dwordx4 v[134:137], v[42:43], off
	global_load_dwordx4 v[138:141], v[122:123], off
	v_add_co_u32_e32 v42, vcc, 0x180000, v22
	s_nop 0
	s_nop 1
	v_addc_co_u32_e32 v43, vcc, 0, v23, vcc
	v_add_co_u32_e32 v22, vcc, 0x1c0000, v22
	global_load_dwordx4 v[142:145], v[42:43], off
	s_nop 0
	v_addc_co_u32_e32 v23, vcc, 0, v23, vcc
	global_load_dwordx4 v[146:149], v[22:23], off
	s_waitcnt vmcnt(7)
	v_pk_fma_f32 v[10:11], v[10:11], s[2:3], v[16:17] op_sel_hi:[1,0,1]
	v_pk_fma_f32 v[8:9], v[8:9], s[2:3], v[14:15] op_sel_hi:[1,0,1]
	s_waitcnt vmcnt(6)
	v_pk_add_f32 v[10:11], v[10:11], v[20:21]
	v_pk_add_f32 v[8:9], v[8:9], v[18:19]
	s_waitcnt vmcnt(5)
	v_pk_add_f32 v[10:11], v[10:11], v[30:31]
	v_pk_add_f32 v[8:9], v[8:9], v[28:29]
	s_waitcnt vmcnt(4)
	v_pk_add_f32 v[10:11], v[10:11], v[132:133]
	v_pk_add_f32 v[8:9], v[8:9], v[130:131]
	s_waitcnt vmcnt(3)
	v_pk_add_f32 v[10:11], v[10:11], v[136:137]
	v_pk_add_f32 v[8:9], v[8:9], v[134:135]
	s_waitcnt vmcnt(2)
	v_pk_add_f32 v[10:11], v[10:11], v[140:141]
	v_pk_add_f32 v[8:9], v[8:9], v[138:139]
	s_waitcnt vmcnt(1)
	v_pk_add_f32 v[10:11], v[10:11], v[144:145]
	v_pk_add_f32 v[8:9], v[8:9], v[142:143]
	s_waitcnt vmcnt(0)
	v_pk_add_f32 v[10:11], v[10:11], v[148:149]
	v_pk_add_f32 v[8:9], v[8:9], v[146:147]

; __device__ __forceinline__ void ln_load_row(const Params& p, const float* src, int which, int r, int lane, f32x4 (&x)[8]) {
;     ...
;     const int wg = gid * 64 + k * gsz + (pm - fm), off = wg % 36, xcd = wg / 36;
;     if (off >= 32) {
;       const int j = (off - 32) * 8 + xcd;
;       f32x4 v = *(const f32x4*)(rs + 256 * k + 4 * lane) * ALPHA;
;       const float* pp = part + (size_t)j * 8 * 65536 + (r & 255) * 256 + 4 * lane;
;       f32x4 t[8];
; #pragma unroll
;       for (int q = 0; q < 8; ++q) t[q] = *(const f32x4*)(pp + (size_t)q * 65536);
; #pragma unroll
;       for (int q = 0; q < 8; ++q) v += t[q];
;       x[k] = v;
.LBB0_139:
	s_andn2_saveexec_b64 s[38:39], s[38:39]
	s_cbranch_execz .LBB0_141
	v_lshlrev_b32_e32 v12, 3, v18
	s_movk_i32 s29, 0xff00
	v_add3_u32 v18, v17, v12, s29
	v_ashrrev_i32_e32 v19, 31, v18
	v_lshlrev_b64 v[18:19], 21, v[18:19]
	v_lshl_add_u64 v[22:23], v[120:121], 0, v[18:19]
	v_add_co_u32_e32 v28, vcc, 0x40000, v22
	global_load_dwordx4 v[12:15], v[118:119], off offset:3072
	s_nop 0
	v_addc_co_u32_e32 v29, vcc, 0, v23, vcc
	v_add_co_u32_e32 v42, vcc, 0x80000, v22
	global_load_dwordx4 v[18:21], v[22:23], off
	s_nop 0
	global_load_dwordx4 v[28:31], v[28:29], off
	v_addc_co_u32_e32 v43, vcc, 0, v23, vcc
	v_add_co_u32_e32 v122, vcc, 0xc0000, v22
	s_nop 1
	v_addc_co_u32_e32 v123, vcc, 0, v23, vcc
	global_load_dwordx4 v[130:133], v[42:43], off
	global_load_dwordx4 v[134:137], v[122:123], off
	v_add_co_u32_e32 v42, vcc, 0x100000, v22
	s_nop 0
	s_nop 1
	v_addc_co_u32_e32 v43, vcc, 0, v23, vcc
	v_add_co_u32_e32 v122, vcc, 0x140000, v22
	s_nop 1
	v_addc_co_u32_e32 v123, vcc, 0, v23, vcc
	global_load_dwordx4 v[138:141], v[42:43], off
	global_load_dwordx4 v[142:145], v[122:123], off
	v_add_co_u32_e32 v42, vcc, 0x180000, v22
	s_nop 0
	s_nop 1
	v_addc_co_u32_e32 v43, vcc, 0, v23, vcc
	v_add_co_u32_e32 v22, vcc, 0x1c0000, v22
	global_load_dwordx4 v[146:149], v[42:43], off
	s_nop 0
	v_addc_co_u32_e32 v23, vcc, 0, v23, vcc
	global_load_dwordx4 v[150:153], v[22:23], off
	s_waitcnt vmcnt(7)
	v_pk_fma_f32 v[14:15], v[14:15], s[2:3], v[20:21] op_sel_hi:[1,0,1]
	v_pk_fma_f32 v[12:13], v[12:13], s[2:3], v[18:19] op_sel_hi:[1,0,1]
	s_waitcnt vmcnt(6)
	v_pk_add_f32 v[14:15], v[14:15], v[30:31]
	v_pk_add_f32 v[12:13], v[12:13], v[28:29]
	s_waitcnt vmcnt(5)
	v_pk_add_f32 v[14:15], v[14:15], v[132:133]
	v_pk_add_f32 v[12:13], v[12:13], v[130:131]
	s_waitcnt vmcnt(4)
	v_pk_add_f32 v[14:15], v[14:15], v[136:137]
	v_pk_add_f32 v[12:13], v[12:13], v[134:135]
	s_waitcnt vmcnt(3)
	v_pk_add_f32 v[14:15], v[14:15], v[140:141]
	v_pk_add_f32 v[12:13], v[12:13], v[138:139]
	s_waitcnt vmcnt(2)
	v_pk_add_f32 v[14:15], v[14:15], v[144:145]
	v_pk_add_f32 v[12:13], v[12:13], v[142:143]
	s_waitcnt vmcnt(1)
	v_pk_add_f32 v[14:15], v[14:15], v[148:149]
	v_pk_add_f32 v[12:13], v[12:13], v[146:147]
	s_waitcnt vmcnt(0)
	v_pk_add_f32 v[14:15], v[14:15], v[152:153]
	v_pk_add_f32 v[12:13], v[12:13], v[150:151]

; __device__ __forceinline__ void ln_load_row(const Params& p, const float* src, int which, int r, int lane, f32x4 (&x)[8]) {
;     ...
;     const int wg = gid * 64 + k * gsz + (pm - fm), off = wg % 36, xcd = wg / 36;
;     if (off >= 32) {
;       const int j = (off - 32) * 8 + xcd;
;       f32x4 v = *(const f32x4*)(rs + 256 * k + 4 * lane) * ALPHA;
;       const float* pp = part + (size_t)j * 8 * 65536 + (r & 255) * 256 + 4 * lane;
;       f32x4 t[8];
; #pragma unroll
;       for (int q = 0; q < 8; ++q) t[q] = *(const f32x4*)(pp + (size_t)q * 65536);
; #pragma unroll
;       for (int q = 0; q < 8; ++q) v += t[q];
;       x[k] = v;
.LBB0_143:
	s_andn2_saveexec_b64 s[38:39], s[38:39]
	s_cbranch_execz .LBB0_145
	v_lshlrev_b32_e32 v16, 3, v22
	s_movk_i32 s29, 0xff00
	v_add3_u32 v22, v21, v16, s29
	v_ashrrev_i32_e32 v23, 31, v22
	v_add_co_u32_e32 v16, vcc, 0x1000, v118
	v_lshlrev_b64 v[22:23], 21, v[22:23]
	s_nop 0
	v_addc_co_u32_e32 v17, vcc, 0, v119, vcc
	v_lshl_add_u64 v[22:23], v[120:121], 0, v[22:23]
	v_add_co_u32_e32 v42, vcc, 0x40000, v22
	global_load_dwordx4 v[16:19], v[16:17], off
	s_nop 0
	v_addc_co_u32_e32 v43, vcc, 0, v23, vcc
	global_load_dwordx4 v[28:31], v[22:23], off
	global_load_dwordx4 v[130:133], v[42:43], off
	v_add_co_u32_e32 v42, vcc, 0x80000, v22
	s_nop 1
	v_addc_co_u32_e32 v43, vcc, 0, v23, vcc
	v_add_co_u32_e32 v122, vcc, 0xc0000, v22
	s_nop 0
	s_nop 1
	v_addc_co_u32_e32 v123, vcc, 0, v23, vcc
	global_load_dwordx4 v[134:137], v[42:43], off
	global_load_dwordx4 v[138:141], v[122:123], off
	v_add_co_u32_e32 v42, vcc, 0x100000, v22
	s_nop 1
	v_addc_co_u32_e32 v43, vcc, 0, v23, vcc
	v_add_co_u32_e32 v122, vcc, 0x140000, v22
	s_nop 0
	s_nop 1
	v_addc_co_u32_e32 v123, vcc, 0, v23, vcc
	global_load_dwordx4 v[142:145], v[42:43], off
	global_load_dwordx4 v[146:149], v[122:123], off
	v_add_co_u32_e32 v42, vcc, 0x180000, v22
	s_nop 1
	v_addc_co_u32_e32 v43, vcc, 0, v23, vcc
	v_add_co_u32_e32 v22, vcc, 0x1c0000, v22
	global_load_dwordx4 v[150:153], v[42:43], off
	s_nop 0
	v_addc_co_u32_e32 v23, vcc, 0, v23, vcc
	global_load_dwordx4 v[154:157], v[22:23], off
	s_waitcnt vmcnt(7)
	v_pk_fma_f32 v[18:19], v[18:19], s[2:3], v[30:31] op_sel_hi:[1,0,1]
	v_pk_fma_f32 v[16:17], v[16:17], s[2:3], v[28:29] op_sel_hi:[1,0,1]
	s_waitcnt vmcnt(6)
	v_pk_add_f32 v[18:19], v[18:19], v[132:133]
	v_pk_add_f32 v[16:17], v[16:17], v[130:131]
	s_waitcnt vmcnt(5)
	v_pk_add_f32 v[18:19], v[18:19], v[136:137]
	v_pk_add_f32 v[16:17], v[16:17], v[134:135]
	s_waitcnt vmcnt(4)
	v_pk_add_f32 v[18:19], v[18:19], v[140:141]
	v_pk_add_f32 v[16:17], v[16:17], v[138:139]
	s_waitcnt vmcnt(3)
	v_pk_add_f32 v[18:19], v[18:19], v[144:145]
	v_pk_add_f32 v[16:17], v[16:17], v[142:143]
	s_waitcnt vmcnt(2)
	v_pk_add_f32 v[18:19], v[18:19], v[148:149]
	v_pk_add_f32 v[16:17], v[16:17], v[146:147]
	s_waitcnt vmcnt(1)
	v_pk_add_f32 v[18:19], v[18:19], v[152:153]
	v_pk_add_f32 v[16:17], v[16:17], v[150:151]
	s_waitcnt vmcnt(0)
	v_pk_add_f32 v[18:19], v[18:19], v[156:157]
	v_pk_add_f32 v[16:17], v[16:17], v[154:155]

; __device__ __forceinline__ void ln_load_row(const Params& p, const float* src, int which, int r, int lane, f32x4 (&x)[8]) {
;     ...
;     const int wg = gid * 64 + k * gsz + (pm - fm), off = wg % 36, xcd = wg / 36;
;     if (off >= 32) {
;       const int j = (off - 32) * 8 + xcd;
;       f32x4 v = *(const f32x4*)(rs + 256 * k + 4 * lane) * ALPHA;
;       const float* pp = part + (size_t)j * 8 * 65536 + (r & 255) * 256 + 4 * lane;
;       f32x4 t[8];
; #pragma unroll
;       for (int q = 0; q < 8; ++q) t[q] = *(const f32x4*)(pp + (size_t)q * 65536);
; #pragma unroll
;       for (int q = 0; q < 8; ++q) v += t[q];
;       x[k] = v;
.LBB0_147:
	s_andn2_saveexec_b64 s[38:39], s[38:39]
	s_cbranch_execz .LBB0_149
	v_lshlrev_b32_e32 v20, 3, v30
	s_movk_i32 s29, 0xff00
	v_add3_u32 v30, v29, v20, s29
	v_ashrrev_i32_e32 v31, 31, v30
	v_add_co_u32_e32 v20, vcc, 0x1000, v118
	v_lshlrev_b64 v[30:31], 21, v[30:31]
	s_nop 0
	v_addc_co_u32_e32 v21, vcc, 0, v119, vcc
	v_lshl_add_u64 v[30:31], v[120:121], 0, v[30:31]
	v_add_co_u32_e32 v42, vcc, 0x40000, v30
	global_load_dwordx4 v[20:23], v[20:21], off offset:1024
	s_nop 0
	v_addc_co_u32_e32 v43, vcc, 0, v31, vcc
	global_load_dwordx4 v[130:133], v[30:31], off
	global_load_dwordx4 v[134:137], v[42:43], off
	v_add_co_u32_e32 v42, vcc, 0x80000, v30
	s_nop 1
	v_addc_co_u32_e32 v43, vcc, 0, v31, vcc
	v_add_co_u32_e32 v122, vcc, 0xc0000, v30
	s_nop 0
	s_nop 1
	v_addc_co_u32_e32 v123, vcc, 0, v31, vcc
	global_load_dwordx4 v[138:141], v[42:43], off
	global_load_dwordx4 v[142:145], v[122:123], off
	v_add_co_u32_e32 v42, vcc, 0x100000, v30
	s_nop 1
	v_addc_co_u32_e32 v43, vcc, 0, v31, vcc
	v_add_co_u32_e32 v122, vcc, 0x140000, v30
	s_nop 0
	s_nop 1
	v_addc_co_u32_e32 v123, vcc, 0, v31, vcc
	global_load_dwordx4 v[146:149], v[42:43], off
	global_load_dwordx4 v[150:153], v[122:123], off
	v_add_co_u32_e32 v42, vcc, 0x180000, v30
	s_nop 1
	v_addc_co_u32_e32 v43, vcc, 0, v31, vcc
	v_add_co_u32_e32 v30, vcc, 0x1c0000, v30
	global_load_dwordx4 v[154:157], v[42:43], off
	s_nop 0
	v_addc_co_u32_e32 v31, vcc, 0, v31, vcc
	global_load_dwordx4 v[158:161], v[30:31], off
	s_waitcnt vmcnt(7)
	v_pk_fma_f32 v[22:23], v[22:23], s[2:3], v[132:133] op_sel_hi:[1,0,1]
	v_pk_fma_f32 v[20:21], v[20:21], s[2:3], v[130:131] op_sel_hi:[1,0,1]
	s_waitcnt vmcnt(6)
	v_pk_add_f32 v[22:23], v[22:23], v[136:137]
	v_pk_add_f32 v[20:21], v[20:21], v[134:135]
	s_waitcnt vmcnt(5)
	v_pk_add_f32 v[22:23], v[22:23], v[140:141]
	v_pk_add_f32 v[20:21], v[20:21], v[138:139]
	s_waitcnt vmcnt(4)
	v_pk_add_f32 v[22:23], v[22:23], v[144:145]
	v_pk_add_f32 v[20:21], v[20:21], v[142:143]
	s_waitcnt vmcnt(3)
	v_pk_add_f32 v[22:23], v[22:23], v[148:149]
	v_pk_add_f32 v[20:21], v[20:21], v[146:147]
	s_waitcnt vmcnt(2)
	v_pk_add_f32 v[22:23], v[22:23], v[152:153]
	v_pk_add_f32 v[20:21], v[20:21], v[150:151]
	s_waitcnt vmcnt(1)
	v_pk_add_f32 v[22:23], v[22:23], v[156:157]
	v_pk_add_f32 v[20:21], v[20:21], v[154:155]
	s_waitcnt vmcnt(0)
	v_pk_add_f32 v[22:23], v[22:23], v[160:161]
	v_pk_add_f32 v[20:21], v[20:21], v[158:159]

; __device__ __forceinline__ void ln_load_row(const Params& p, const float* src, int which, int r, int lane, f32x4 (&x)[8]) {
;     ...
;     const int wg = gid * 64 + k * gsz + (pm - fm), off = wg % 36, xcd = wg / 36;
;     if (off >= 32) {
;       const int j = (off - 32) * 8 + xcd;
;       f32x4 v = *(const f32x4*)(rs + 256 * k + 4 * lane) * ALPHA;
;       const float* pp = part + (size_t)j * 8 * 65536 + (r & 255) * 256 + 4 * lane;
;       f32x4 t[8];
; #pragma unroll
;       for (int q = 0; q < 8; ++q) t[q] = *(const f32x4*)(pp + (size_t)q * 65536);
; #pragma unroll
;       for (int q = 0; q < 8; ++q) v += t[q];
;       x[k] = v;
.LBB0_151:
	s_andn2_saveexec_b64 s[38:39], s[38:39]
	s_cbranch_execz .LBB0_153
	v_lshlrev_b32_e32 v28, 3, v43
	s_movk_i32 s29, 0xff00
	v_add3_u32 v42, v42, v28, s29
	v_ashrrev_i32_e32 v43, 31, v42
	v_add_co_u32_e32 v28, vcc, 0x1000, v118
	v_lshlrev_b64 v[42:43], 21, v[42:43]
	s_nop 0
	v_addc_co_u32_e32 v29, vcc, 0, v119, vcc
	v_lshl_add_u64 v[42:43], v[120:121], 0, v[42:43]
	v_add_co_u32_e32 v122, vcc, 0x40000, v42
	global_load_dwordx4 v[28:31], v[28:29], off offset:2048
	s_nop 0
	v_addc_co_u32_e32 v123, vcc, 0, v43, vcc
	global_load_dwordx4 v[130:133], v[42:43], off
	global_load_dwordx4 v[134:137], v[122:123], off
	v_add_co_u32_e32 v122, vcc, 0x80000, v42
	s_nop 1
	v_addc_co_u32_e32 v123, vcc, 0, v43, vcc
	v_add_co_u32_e32 v142, vcc, 0xc0000, v42
	s_nop 0
	s_nop 1
	v_addc_co_u32_e32 v143, vcc, 0, v43, vcc
	global_load_dwordx4 v[138:141], v[122:123], off
	s_nop 0
	global_load_dwordx4 v[142:145], v[142:143], off
	v_add_co_u32_e32 v122, vcc, 0x100000, v42
	s_nop 1
	v_addc_co_u32_e32 v123, vcc, 0, v43, vcc
	v_add_co_u32_e32 v150, vcc, 0x140000, v42
	s_nop 0
	s_nop 1
	v_addc_co_u32_e32 v151, vcc, 0, v43, vcc
	global_load_dwordx4 v[146:149], v[122:123], off
	s_nop 0
	global_load_dwordx4 v[150:153], v[150:151], off
	v_add_co_u32_e32 v122, vcc, 0x180000, v42
	s_nop 1
	v_addc_co_u32_e32 v123, vcc, 0, v43, vcc
	v_add_co_u32_e32 v42, vcc, 0x1c0000, v42
	global_load_dwordx4 v[154:157], v[122:123], off
	s_nop 0
	v_addc_co_u32_e32 v43, vcc, 0, v43, vcc
	global_load_dwordx4 v[158:161], v[42:43], off
	s_waitcnt vmcnt(7)
	v_pk_fma_f32 v[30:31], v[30:31], s[2:3], v[132:133] op_sel_hi:[1,0,1]
	v_pk_fma_f32 v[28:29], v[28:29], s[2:3], v[130:131] op_sel_hi:[1,0,1]
	s_waitcnt vmcnt(6)
	v_pk_add_f32 v[30:31], v[30:31], v[136:137]
	v_pk_add_f32 v[28:29], v[28:29], v[134:135]
	s_waitcnt vmcnt(5)
	v_pk_add_f32 v[30:31], v[30:31], v[140:141]
	v_pk_add_f32 v[28:29], v[28:29], v[138:139]
	s_waitcnt vmcnt(4)
	v_pk_add_f32 v[30:31], v[30:31], v[144:145]
	v_pk_add_f32 v[28:29], v[28:29], v[142:143]
	s_waitcnt vmcnt(3)
	v_pk_add_f32 v[30:31], v[30:31], v[148:149]
	v_pk_add_f32 v[28:29], v[28:29], v[146:147]
	s_waitcnt vmcnt(2)
	v_pk_add_f32 v[30:31], v[30:31], v[152:153]
	v_pk_add_f32 v[28:29], v[28:29], v[150:151]
	s_waitcnt vmcnt(1)
	v_pk_add_f32 v[30:31], v[30:31], v[156:157]
	v_pk_add_f32 v[28:29], v[28:29], v[154:155]
	s_waitcnt vmcnt(0)
	v_pk_add_f32 v[30:31], v[30:31], v[160:161]
	v_pk_add_f32 v[28:29], v[28:29], v[158:159]

; __device__ __forceinline__ void ln_load_row(const Params& p, const float* src, int which, int r, int lane, f32x4 (&x)[8]) {
;     ...
;     const int wg = gid * 64 + k * gsz + (pm - fm), off = wg % 36, xcd = wg / 36;
;     if (off >= 32) {
;       const int j = (off - 32) * 8 + xcd;
;       f32x4 v = *(const f32x4*)(rs + 256 * k + 4 * lane) * ALPHA;
;       const float* pp = part + (size_t)j * 8 * 65536 + (r & 255) * 256 + 4 * lane;
;       f32x4 t[8];
; #pragma unroll
;       for (int q = 0; q < 8; ++q) t[q] = *(const f32x4*)(pp + (size_t)q * 65536);
; #pragma unroll
;       for (int q = 0; q < 8; ++q) v += t[q];
;       x[k] = v;
.LBB0_155:
	s_andn2_saveexec_b64 s[38:39], s[38:39]
	s_cbranch_execz .LBB0_157
	v_lshlrev_b32_e32 v40, 3, v103
	s_movk_i32 s29, 0xff00
	v_add3_u32 v116, v67, v40, s29
	v_ashrrev_i32_e32 v117, 31, v116
	v_add_co_u32_e32 v40, vcc, 0x1000, v118
	v_lshlrev_b64 v[116:117], 21, v[116:117]
	s_nop 0
	v_addc_co_u32_e32 v41, vcc, 0, v119, vcc
	v_lshl_add_u64 v[150:151], v[120:121], 0, v[116:117]
	v_add_co_u32_e32 v120, vcc, 0x40000, v150
	global_load_dwordx4 v[40:43], v[40:41], off offset:3072
	s_nop 0
	v_addc_co_u32_e32 v121, vcc, 0, v151, vcc
	v_add_co_u32_e32 v130, vcc, 0x80000, v150
	global_load_dwordx4 v[116:119], v[150:151], off
	s_nop 0
	global_load_dwordx4 v[120:123], v[120:121], off
	v_addc_co_u32_e32 v131, vcc, 0, v151, vcc
	v_add_co_u32_e32 v134, vcc, 0xc0000, v150
	s_nop 1
	v_addc_co_u32_e32 v135, vcc, 0, v151, vcc
	v_add_co_u32_e32 v138, vcc, 0x100000, v150
	global_load_dwordx4 v[130:133], v[130:131], off
	s_nop 0
	global_load_dwordx4 v[134:137], v[134:135], off
	v_addc_co_u32_e32 v139, vcc, 0, v151, vcc
	v_add_co_u32_e32 v142, vcc, 0x140000, v150
	s_nop 0
	s_nop 1
	v_addc_co_u32_e32 v143, vcc, 0, v151, vcc
	v_add_co_u32_e32 v146, vcc, 0x180000, v150
	global_load_dwordx4 v[138:141], v[138:139], off
	s_nop 0
	global_load_dwordx4 v[142:145], v[142:143], off
	v_addc_co_u32_e32 v147, vcc, 0, v151, vcc
	v_add_co_u32_e32 v150, vcc, 0x1c0000, v150
	global_load_dwordx4 v[146:149], v[146:147], off
	s_nop 0
	v_addc_co_u32_e32 v151, vcc, 0, v151, vcc
	global_load_dwordx4 v[150:153], v[150:151], off
	s_waitcnt vmcnt(7)
	v_pk_fma_f32 v[42:43], v[42:43], s[2:3], v[118:119] op_sel_hi:[1,0,1]
	v_pk_fma_f32 v[40:41], v[40:41], s[2:3], v[116:117] op_sel_hi:[1,0,1]
	s_waitcnt vmcnt(6)
	v_pk_add_f32 v[42:43], v[42:43], v[122:123]
	v_pk_add_f32 v[40:41], v[40:41], v[120:121]
	s_waitcnt vmcnt(5)
	v_pk_add_f32 v[42:43], v[42:43], v[132:133]
	v_pk_add_f32 v[40:41], v[40:41], v[130:131]
	s_waitcnt vmcnt(4)
	v_pk_add_f32 v[42:43], v[42:43], v[136:137]
	v_pk_add_f32 v[40:41], v[40:41], v[134:135]
	s_waitcnt vmcnt(3)
	v_pk_add_f32 v[42:43], v[42:43], v[140:141]
	v_pk_add_f32 v[40:41], v[40:41], v[138:139]
	s_waitcnt vmcnt(2)
	v_pk_add_f32 v[42:43], v[42:43], v[144:145]
	v_pk_add_f32 v[40:41], v[40:41], v[142:143]
	s_waitcnt vmcnt(1)
	v_pk_add_f32 v[42:43], v[42:43], v[148:149]
	v_pk_add_f32 v[40:41], v[40:41], v[146:147]
	s_waitcnt vmcnt(0)
	v_pk_add_f32 v[42:43], v[42:43], v[152:153]
	v_pk_add_f32 v[40:41], v[40:41], v[150:151]

; __device__ __forceinline__ void ln_load_row(const Params& p, const float* src, int which, int r, int lane, f32x4 (&x)[8]) {
;     ...
;     const int wg = gid * 64 + k * gsz + (pm - fm), off = wg % 36, xcd = wg / 36;
;     if (off >= 32) {
;       const int j = (off - 32) * 8 + xcd;
;       f32x4 v = *(const f32x4*)(rs + 256 * k + 4 * lane) * ALPHA;
;       const float* pp = part + (size_t)j * 8 * 65536 + (r & 255) * 256 + 4 * lane;
;       f32x4 t[8];
; #pragma unroll
;       for (int q = 0; q < 8; ++q) t[q] = *(const f32x4*)(pp + (size_t)q * 65536);
; #pragma unroll
;       for (int q = 0; q < 8; ++q) v += t[q];
;       x[k] = v;
.LBB0_1497:
	s_or_saveexec_b64 s[36:37], s[36:37]
	v_and_b32_e32 v36, 0xff00, v126
	v_lshlrev_b32_e32 v64, 2, v36
	v_lshl_add_u64 v[112:113], v[92:93], 0, v[64:65]
	s_xor_b64 exec, exec, s[36:37]
	s_cbranch_execz .LBB0_1499
	v_lshlrev_b32_e32 v20, 3, v31
	s_movk_i32 s29, 0xff00
	v_add3_u32 v30, v30, v20, s29
	v_ashrrev_i32_e32 v31, 31, v30
	v_add_co_u32_e32 v20, vcc, 0x109000, v110
	v_lshlrev_b64 v[30:31], 21, v[30:31]
	s_nop 0
	v_addc_co_u32_e32 v21, vcc, 0, v111, vcc
	v_lshl_add_u64 v[30:31], v[112:113], 0, v[30:31]
	v_add_co_u32_e32 v44, vcc, 0x40000, v30
	global_load_dwordx4 v[20:23], v[20:21], off
	s_nop 0
	v_addc_co_u32_e32 v45, vcc, 0, v31, vcc
	v_add_co_u32_e32 v48, vcc, 0x80000, v30
	global_load_dwordx4 v[36:39], v[30:31], off
	s_nop 0
	global_load_dwordx4 v[44:47], v[44:45], off
	v_addc_co_u32_e32 v49, vcc, 0, v31, vcc
	v_add_co_u32_e32 v52, vcc, 0xc0000, v30
	s_nop 1
	v_addc_co_u32_e32 v53, vcc, 0, v31, vcc
	v_add_co_u32_e32 v56, vcc, 0x100000, v30
	global_load_dwordx4 v[48:51], v[48:49], off
	s_nop 0
	global_load_dwordx4 v[52:55], v[52:53], off
	v_addc_co_u32_e32 v57, vcc, 0, v31, vcc
	v_add_co_u32_e32 v60, vcc, 0x140000, v30
	s_nop 0
	s_nop 1
	v_addc_co_u32_e32 v61, vcc, 0, v31, vcc
	v_add_co_u32_e32 v114, vcc, 0x180000, v30
	global_load_dwordx4 v[56:59], v[56:57], off
	s_nop 0
	global_load_dwordx4 v[60:63], v[60:61], off
	v_addc_co_u32_e32 v115, vcc, 0, v31, vcc
	v_add_co_u32_e32 v30, vcc, 0x1c0000, v30
	global_load_dwordx4 v[114:117], v[114:115], off
	s_nop 0
	v_addc_co_u32_e32 v31, vcc, 0, v31, vcc
	global_load_dwordx4 v[128:131], v[30:31], off
	s_waitcnt vmcnt(7)
	v_pk_fma_f32 v[22:23], v[22:23], s[2:3], v[38:39] op_sel_hi:[1,0,1]
	v_pk_fma_f32 v[20:21], v[20:21], s[2:3], v[36:37] op_sel_hi:[1,0,1]
	s_waitcnt vmcnt(6)
	v_pk_add_f32 v[22:23], v[22:23], v[46:47]
	v_pk_add_f32 v[20:21], v[20:21], v[44:45]
	s_waitcnt vmcnt(5)
	v_pk_add_f32 v[22:23], v[22:23], v[50:51]
	v_pk_add_f32 v[20:21], v[20:21], v[48:49]
	s_waitcnt vmcnt(4)
	v_pk_add_f32 v[22:23], v[22:23], v[54:55]
	v_pk_add_f32 v[20:21], v[20:21], v[52:53]
	s_waitcnt vmcnt(3)
	v_pk_add_f32 v[22:23], v[22:23], v[58:59]
	v_pk_add_f32 v[20:21], v[20:21], v[56:57]
	s_waitcnt vmcnt(2)
	v_pk_add_f32 v[22:23], v[22:23], v[62:63]
	v_pk_add_f32 v[20:21], v[20:21], v[60:61]
	s_waitcnt vmcnt(1)
	v_pk_add_f32 v[22:23], v[22:23], v[116:117]
	v_pk_add_f32 v[20:21], v[20:21], v[114:115]
	s_waitcnt vmcnt(0)
	v_pk_add_f32 v[22:23], v[22:23], v[130:131]
	v_pk_add_f32 v[20:21], v[20:21], v[128:129]

; __device__ __forceinline__ void ln_load_row(const Params& p, const float* src, int which, int r, int lane, f32x4 (&x)[8]) {
;     ...
;     const int wg = gid * 64 + k * gsz + (pm - fm), off = wg % 36, xcd = wg / 36;
;     if (off >= 32) {
;       const int j = (off - 32) * 8 + xcd;
;       f32x4 v = *(const f32x4*)(rs + 256 * k + 4 * lane) * ALPHA;
;       const float* pp = part + (size_t)j * 8 * 65536 + (r & 255) * 256 + 4 * lane;
;       f32x4 t[8];
; #pragma unroll
;       for (int q = 0; q < 8; ++q) t[q] = *(const f32x4*)(pp + (size_t)q * 65536);
; #pragma unroll
;       for (int q = 0; q < 8; ++q) v += t[q];
;       x[k] = v;
.LBB0_1501:
	s_andn2_saveexec_b64 s[36:37], s[36:37]
	s_cbranch_execz .LBB0_1503
	v_lshlrev_b32_e32 v28, 3, v38
	s_movk_i32 s29, 0xff00
	v_add3_u32 v38, v37, v28, s29
	v_ashrrev_i32_e32 v39, 31, v38
	v_add_co_u32_e32 v28, vcc, 0x109000, v110
	v_lshlrev_b64 v[38:39], 21, v[38:39]
	s_nop 0
	v_addc_co_u32_e32 v29, vcc, 0, v111, vcc
	v_lshl_add_u64 v[38:39], v[112:113], 0, v[38:39]
	v_add_co_u32_e32 v48, vcc, 0x40000, v38
	global_load_dwordx4 v[28:31], v[28:29], off offset:1024
	s_nop 0
	v_addc_co_u32_e32 v49, vcc, 0, v39, vcc
	v_add_co_u32_e32 v52, vcc, 0x80000, v38
	global_load_dwordx4 v[44:47], v[38:39], off
	s_nop 0
	global_load_dwordx4 v[48:51], v[48:49], off
	v_addc_co_u32_e32 v53, vcc, 0, v39, vcc
	v_add_co_u32_e32 v56, vcc, 0xc0000, v38
	s_nop 1
	v_addc_co_u32_e32 v57, vcc, 0, v39, vcc
	v_add_co_u32_e32 v62, vcc, 0x100000, v38
	global_load_dwordx4 v[52:55], v[52:53], off
	s_nop 0
	global_load_dwordx4 v[56:59], v[56:57], off
	v_addc_co_u32_e32 v63, vcc, 0, v39, vcc
	v_add_co_u32_e32 v118, vcc, 0x140000, v38
	s_nop 0
	s_nop 1
	v_addc_co_u32_e32 v119, vcc, 0, v39, vcc
	global_load_dwordx4 v[114:117], v[62:63], off
	global_load_dwordx4 v[128:131], v[118:119], off
	v_add_co_u32_e32 v62, vcc, 0x180000, v38
	s_nop 0
	s_nop 1
	v_addc_co_u32_e32 v63, vcc, 0, v39, vcc
	v_add_co_u32_e32 v38, vcc, 0x1c0000, v38
	global_load_dwordx4 v[132:135], v[62:63], off
	s_nop 0
	v_addc_co_u32_e32 v39, vcc, 0, v39, vcc
	global_load_dwordx4 v[136:139], v[38:39], off
	s_waitcnt vmcnt(7)
	v_pk_fma_f32 v[30:31], v[30:31], s[2:3], v[46:47] op_sel_hi:[1,0,1]
	v_pk_fma_f32 v[28:29], v[28:29], s[2:3], v[44:45] op_sel_hi:[1,0,1]
	s_waitcnt vmcnt(6)
	v_pk_add_f32 v[30:31], v[30:31], v[50:51]
	v_pk_add_f32 v[28:29], v[28:29], v[48:49]
	s_waitcnt vmcnt(5)
	v_pk_add_f32 v[30:31], v[30:31], v[54:55]
	v_pk_add_f32 v[28:29], v[28:29], v[52:53]
	s_waitcnt vmcnt(4)
	v_pk_add_f32 v[30:31], v[30:31], v[58:59]
	v_pk_add_f32 v[28:29], v[28:29], v[56:57]
	s_waitcnt vmcnt(3)
	v_pk_add_f32 v[30:31], v[30:31], v[116:117]
	v_pk_add_f32 v[28:29], v[28:29], v[114:115]
	s_waitcnt vmcnt(2)
	v_pk_add_f32 v[30:31], v[30:31], v[130:131]
	v_pk_add_f32 v[28:29], v[28:29], v[128:129]
	s_waitcnt vmcnt(1)
	v_pk_add_f32 v[30:31], v[30:31], v[134:135]
	v_pk_add_f32 v[28:29], v[28:29], v[132:133]
	s_waitcnt vmcnt(0)
	v_pk_add_f32 v[30:31], v[30:31], v[138:139]
	v_pk_add_f32 v[28:29], v[28:29], v[136:137]

; __device__ __forceinline__ void ln_load_row(const Params& p, const float* src, int which, int r, int lane, f32x4 (&x)[8]) {
;     ...
;     const int wg = gid * 64 + k * gsz + (pm - fm), off = wg % 36, xcd = wg / 36;
;     if (off >= 32) {
;       const int j = (off - 32) * 8 + xcd;
;       f32x4 v = *(const f32x4*)(rs + 256 * k + 4 * lane) * ALPHA;
;       const float* pp = part + (size_t)j * 8 * 65536 + (r & 255) * 256 + 4 * lane;
;       f32x4 t[8];
; #pragma unroll
;       for (int q = 0; q < 8; ++q) t[q] = *(const f32x4*)(pp + (size_t)q * 65536);
; #pragma unroll
;       for (int q = 0; q < 8; ++q) v += t[q];
;       x[k] = v;
.LBB0_1505:
	s_andn2_saveexec_b64 s[36:37], s[36:37]
	s_cbranch_execz .LBB0_1507
	v_lshlrev_b32_e32 v36, 3, v46
	s_movk_i32 s29, 0xff00
	v_add3_u32 v46, v45, v36, s29
	v_ashrrev_i32_e32 v47, 31, v46
	v_add_co_u32_e32 v36, vcc, 0x109000, v110
	v_lshlrev_b64 v[46:47], 21, v[46:47]
	s_nop 0
	v_addc_co_u32_e32 v37, vcc, 0, v111, vcc
	v_lshl_add_u64 v[58:59], v[112:113], 0, v[46:47]
	v_add_co_u32_e32 v50, vcc, 0x40000, v58
	global_load_dwordx4 v[36:39], v[36:37], off offset:2048
	s_nop 0
	v_addc_co_u32_e32 v51, vcc, 0, v59, vcc
	v_add_co_u32_e32 v54, vcc, 0x80000, v58
	global_load_dwordx4 v[46:49], v[58:59], off
	s_nop 0
	global_load_dwordx4 v[50:53], v[50:51], off
	v_addc_co_u32_e32 v55, vcc, 0, v59, vcc
	v_add_co_u32_e32 v62, vcc, 0xc0000, v58
	s_nop 1
	v_addc_co_u32_e32 v63, vcc, 0, v59, vcc
	global_load_dwordx4 v[54:57], v[54:55], off
	s_nop 0
	global_load_dwordx4 v[114:117], v[62:63], off
	v_add_co_u32_e32 v62, vcc, 0x100000, v58
	s_nop 0
	s_nop 1
	v_addc_co_u32_e32 v63, vcc, 0, v59, vcc
	v_add_co_u32_e32 v118, vcc, 0x140000, v58
	s_nop 0
	s_nop 1
	v_addc_co_u32_e32 v119, vcc, 0, v59, vcc
	global_load_dwordx4 v[128:131], v[62:63], off
	global_load_dwordx4 v[132:135], v[118:119], off
	v_add_co_u32_e32 v62, vcc, 0x180000, v58
	s_nop 0
	s_nop 1
	v_addc_co_u32_e32 v63, vcc, 0, v59, vcc
	v_add_co_u32_e32 v58, vcc, 0x1c0000, v58
	global_load_dwordx4 v[136:139], v[62:63], off
	s_nop 0
	v_addc_co_u32_e32 v59, vcc, 0, v59, vcc
	global_load_dwordx4 v[140:143], v[58:59], off
	s_waitcnt vmcnt(7)
	v_pk_fma_f32 v[38:39], v[38:39], s[2:3], v[48:49] op_sel_hi:[1,0,1]
	v_pk_fma_f32 v[36:37], v[36:37], s[2:3], v[46:47] op_sel_hi:[1,0,1]
	s_waitcnt vmcnt(6)
	v_pk_add_f32 v[38:39], v[38:39], v[52:53]
	v_pk_add_f32 v[36:37], v[36:37], v[50:51]
	s_waitcnt vmcnt(5)
	v_pk_add_f32 v[38:39], v[38:39], v[56:57]
	v_pk_add_f32 v[36:37], v[36:37], v[54:55]
	s_waitcnt vmcnt(4)
	v_pk_add_f32 v[38:39], v[38:39], v[116:117]
	v_pk_add_f32 v[36:37], v[36:37], v[114:115]
	s_waitcnt vmcnt(3)
	v_pk_add_f32 v[38:39], v[38:39], v[130:131]
	v_pk_add_f32 v[36:37], v[36:37], v[128:129]
	s_waitcnt vmcnt(2)
	v_pk_add_f32 v[38:39], v[38:39], v[134:135]
	v_pk_add_f32 v[36:37], v[36:37], v[132:133]
	s_waitcnt vmcnt(1)
	v_pk_add_f32 v[38:39], v[38:39], v[138:139]
	v_pk_add_f32 v[36:37], v[36:37], v[136:137]
	s_waitcnt vmcnt(0)
	v_pk_add_f32 v[38:39], v[38:39], v[142:143]
	v_pk_add_f32 v[36:37], v[36:37], v[140:141]

; __device__ __forceinline__ void ln_load_row(const Params& p, const float* src, int which, int r, int lane, f32x4 (&x)[8]) {
;     ...
;     const int wg = gid * 64 + k * gsz + (pm - fm), off = wg % 36, xcd = wg / 36;
;     if (off >= 32) {
;       const int j = (off - 32) * 8 + xcd;
;       f32x4 v = *(const f32x4*)(rs + 256 * k + 4 * lane) * ALPHA;
;       const float* pp = part + (size_t)j * 8 * 65536 + (r & 255) * 256 + 4 * lane;
;       f32x4 t[8];
; #pragma unroll
;       for (int q = 0; q < 8; ++q) t[q] = *(const f32x4*)(pp + (size_t)q * 65536);
; #pragma unroll
;       for (int q = 0; q < 8; ++q) v += t[q];
;       x[k] = v;
.LBB0_1509:
	s_andn2_saveexec_b64 s[36:37], s[36:37]
	s_cbranch_execz .LBB0_1511
	v_lshlrev_b32_e32 v44, 3, v50
	s_movk_i32 s29, 0xff00
	v_add3_u32 v50, v49, v44, s29
	v_ashrrev_i32_e32 v51, 31, v50
	v_add_co_u32_e32 v44, vcc, 0x109000, v110
	v_lshlrev_b64 v[50:51], 21, v[50:51]
	s_nop 0
	v_addc_co_u32_e32 v45, vcc, 0, v111, vcc
	v_lshl_add_u64 v[58:59], v[112:113], 0, v[50:51]
	v_add_co_u32_e32 v54, vcc, 0x40000, v58
	global_load_dwordx4 v[44:47], v[44:45], off offset:3072
	s_nop 0
	v_addc_co_u32_e32 v55, vcc, 0, v59, vcc
	v_add_co_u32_e32 v62, vcc, 0x80000, v58
	global_load_dwordx4 v[50:53], v[58:59], off
	s_nop 0
	global_load_dwordx4 v[54:57], v[54:55], off
	v_addc_co_u32_e32 v63, vcc, 0, v59, vcc
	v_add_co_u32_e32 v118, vcc, 0xc0000, v58
	s_nop 1
	v_addc_co_u32_e32 v119, vcc, 0, v59, vcc
	global_load_dwordx4 v[114:117], v[62:63], off
	global_load_dwordx4 v[128:131], v[118:119], off
	v_add_co_u32_e32 v62, vcc, 0x100000, v58
	s_nop 0
	s_nop 1
	v_addc_co_u32_e32 v63, vcc, 0, v59, vcc
	v_add_co_u32_e32 v118, vcc, 0x140000, v58
	s_nop 0
	s_nop 1
	v_addc_co_u32_e32 v119, vcc, 0, v59, vcc
	global_load_dwordx4 v[132:135], v[62:63], off
	global_load_dwordx4 v[136:139], v[118:119], off
	v_add_co_u32_e32 v62, vcc, 0x180000, v58
	s_nop 0
	s_nop 1
	v_addc_co_u32_e32 v63, vcc, 0, v59, vcc
	v_add_co_u32_e32 v58, vcc, 0x1c0000, v58
	global_load_dwordx4 v[140:143], v[62:63], off
	s_nop 0
	v_addc_co_u32_e32 v59, vcc, 0, v59, vcc
	global_load_dwordx4 v[144:147], v[58:59], off
	s_waitcnt vmcnt(7)
	v_pk_fma_f32 v[46:47], v[46:47], s[2:3], v[52:53] op_sel_hi:[1,0,1]
	v_pk_fma_f32 v[44:45], v[44:45], s[2:3], v[50:51] op_sel_hi:[1,0,1]
	s_waitcnt vmcnt(6)
	v_pk_add_f32 v[46:47], v[46:47], v[56:57]
	v_pk_add_f32 v[44:45], v[44:45], v[54:55]
	s_waitcnt vmcnt(5)
	v_pk_add_f32 v[46:47], v[46:47], v[116:117]
	v_pk_add_f32 v[44:45], v[44:45], v[114:115]
	s_waitcnt vmcnt(4)
	v_pk_add_f32 v[46:47], v[46:47], v[130:131]
	v_pk_add_f32 v[44:45], v[44:45], v[128:129]
	s_waitcnt vmcnt(3)
	v_pk_add_f32 v[46:47], v[46:47], v[134:135]
	v_pk_add_f32 v[44:45], v[44:45], v[132:133]
	s_waitcnt vmcnt(2)
	v_pk_add_f32 v[46:47], v[46:47], v[138:139]
	v_pk_add_f32 v[44:45], v[44:45], v[136:137]
	s_waitcnt vmcnt(1)
	v_pk_add_f32 v[46:47], v[46:47], v[142:143]
	v_pk_add_f32 v[44:45], v[44:45], v[140:141]
	s_waitcnt vmcnt(0)
	v_pk_add_f32 v[46:47], v[46:47], v[146:147]
	v_pk_add_f32 v[44:45], v[44:45], v[144:145]

; __device__ __forceinline__ void ln_load_row(const Params& p, const float* src, int which, int r, int lane, f32x4 (&x)[8]) {
;     ...
;     const int wg = gid * 64 + k * gsz + (pm - fm), off = wg % 36, xcd = wg / 36;
;     if (off >= 32) {
;       const int j = (off - 32) * 8 + xcd;
;       f32x4 v = *(const f32x4*)(rs + 256 * k + 4 * lane) * ALPHA;
;       const float* pp = part + (size_t)j * 8 * 65536 + (r & 255) * 256 + 4 * lane;
;       f32x4 t[8];
; #pragma unroll
;       for (int q = 0; q < 8; ++q) t[q] = *(const f32x4*)(pp + (size_t)q * 65536);
; #pragma unroll
;       for (int q = 0; q < 8; ++q) v += t[q];
;       x[k] = v;
.LBB0_1513:
	s_andn2_saveexec_b64 s[36:37], s[36:37]
	s_cbranch_execz .LBB0_1515
	v_lshlrev_b32_e32 v48, 3, v54
	s_movk_i32 s29, 0xff00
	v_add3_u32 v54, v53, v48, s29
	v_ashrrev_i32_e32 v55, 31, v54
	v_add_co_u32_e32 v48, vcc, 0x10a000, v110
	v_lshlrev_b64 v[54:55], 21, v[54:55]
	s_nop 0
	v_addc_co_u32_e32 v49, vcc, 0, v111, vcc
	v_lshl_add_u64 v[58:59], v[112:113], 0, v[54:55]
	v_add_co_u32_e32 v62, vcc, 0x40000, v58
	global_load_dwordx4 v[48:51], v[48:49], off
	s_nop 0
	v_addc_co_u32_e32 v63, vcc, 0, v59, vcc
	global_load_dwordx4 v[54:57], v[58:59], off
	global_load_dwordx4 v[114:117], v[62:63], off
	v_add_co_u32_e32 v62, vcc, 0x80000, v58
	s_nop 1
	v_addc_co_u32_e32 v63, vcc, 0, v59, vcc
	v_add_co_u32_e32 v118, vcc, 0xc0000, v58
	s_nop 0
	s_nop 1
	v_addc_co_u32_e32 v119, vcc, 0, v59, vcc
	global_load_dwordx4 v[128:131], v[62:63], off
	global_load_dwordx4 v[132:135], v[118:119], off
	v_add_co_u32_e32 v62, vcc, 0x100000, v58
	s_nop 0
	s_nop 1
	v_addc_co_u32_e32 v63, vcc, 0, v59, vcc
	v_add_co_u32_e32 v118, vcc, 0x140000, v58
	s_nop 0
	s_nop 1
	v_addc_co_u32_e32 v119, vcc, 0, v59, vcc
	global_load_dwordx4 v[136:139], v[62:63], off
	global_load_dwordx4 v[140:143], v[118:119], off
	v_add_co_u32_e32 v62, vcc, 0x180000, v58
	s_nop 1
	v_addc_co_u32_e32 v63, vcc, 0, v59, vcc
	v_add_co_u32_e32 v58, vcc, 0x1c0000, v58
	global_load_dwordx4 v[144:147], v[62:63], off
	s_nop 0
	v_addc_co_u32_e32 v59, vcc, 0, v59, vcc
	global_load_dwordx4 v[148:151], v[58:59], off
	s_waitcnt vmcnt(7)
	v_pk_fma_f32 v[50:51], v[50:51], s[2:3], v[56:57] op_sel_hi:[1,0,1]
	v_pk_fma_f32 v[48:49], v[48:49], s[2:3], v[54:55] op_sel_hi:[1,0,1]
	s_waitcnt vmcnt(6)
	v_pk_add_f32 v[50:51], v[50:51], v[116:117]
	v_pk_add_f32 v[48:49], v[48:49], v[114:115]
	s_waitcnt vmcnt(5)
	v_pk_add_f32 v[50:51], v[50:51], v[130:131]
	v_pk_add_f32 v[48:49], v[48:49], v[128:129]
	s_waitcnt vmcnt(4)
	v_pk_add_f32 v[50:51], v[50:51], v[134:135]
	v_pk_add_f32 v[48:49], v[48:49], v[132:133]
	s_waitcnt vmcnt(3)
	v_pk_add_f32 v[50:51], v[50:51], v[138:139]
	v_pk_add_f32 v[48:49], v[48:49], v[136:137]
	s_waitcnt vmcnt(2)
	v_pk_add_f32 v[50:51], v[50:51], v[142:143]
	v_pk_add_f32 v[48:49], v[48:49], v[140:141]
	s_waitcnt vmcnt(1)
	v_pk_add_f32 v[50:51], v[50:51], v[146:147]
	v_pk_add_f32 v[48:49], v[48:49], v[144:145]
	s_waitcnt vmcnt(0)
	v_pk_add_f32 v[50:51], v[50:51], v[150:151]
	v_pk_add_f32 v[48:49], v[48:49], v[148:149]

; __device__ __forceinline__ void ln_load_row(const Params& p, const float* src, int which, int r, int lane, f32x4 (&x)[8]) {
;     ...
;     const int wg = gid * 64 + k * gsz + (pm - fm), off = wg % 36, xcd = wg / 36;
;     if (off >= 32) {
;       const int j = (off - 32) * 8 + xcd;
;       f32x4 v = *(const f32x4*)(rs + 256 * k + 4 * lane) * ALPHA;
;       const float* pp = part + (size_t)j * 8 * 65536 + (r & 255) * 256 + 4 * lane;
;       f32x4 t[8];
; #pragma unroll
;       for (int q = 0; q < 8; ++q) t[q] = *(const f32x4*)(pp + (size_t)q * 65536);
; #pragma unroll
;       for (int q = 0; q < 8; ++q) v += t[q];
;       x[k] = v;
.LBB0_1517:
	s_andn2_saveexec_b64 s[36:37], s[36:37]
	s_cbranch_execz .LBB0_1519
	v_lshlrev_b32_e32 v52, 3, v58
	s_movk_i32 s29, 0xff00
	v_add3_u32 v58, v57, v52, s29
	v_ashrrev_i32_e32 v59, 31, v58
	v_add_co_u32_e32 v52, vcc, 0x10a000, v110
	v_lshlrev_b64 v[58:59], 21, v[58:59]
	s_nop 0
	v_addc_co_u32_e32 v53, vcc, 0, v111, vcc
	v_lshl_add_u64 v[58:59], v[112:113], 0, v[58:59]
	v_add_co_u32_e32 v62, vcc, 0x40000, v58
	global_load_dwordx4 v[52:55], v[52:53], off offset:1024
	s_nop 0
	v_addc_co_u32_e32 v63, vcc, 0, v59, vcc
	global_load_dwordx4 v[114:117], v[58:59], off
	global_load_dwordx4 v[128:131], v[62:63], off
	v_add_co_u32_e32 v62, vcc, 0x80000, v58
	s_nop 1
	v_addc_co_u32_e32 v63, vcc, 0, v59, vcc
	v_add_co_u32_e32 v118, vcc, 0xc0000, v58
	s_nop 0
	s_nop 1
	v_addc_co_u32_e32 v119, vcc, 0, v59, vcc
	global_load_dwordx4 v[132:135], v[62:63], off
	global_load_dwordx4 v[136:139], v[118:119], off
	v_add_co_u32_e32 v62, vcc, 0x100000, v58
	s_nop 0
	s_nop 1
	v_addc_co_u32_e32 v63, vcc, 0, v59, vcc
	v_add_co_u32_e32 v118, vcc, 0x140000, v58
	s_nop 0
	s_nop 1
	v_addc_co_u32_e32 v119, vcc, 0, v59, vcc
	global_load_dwordx4 v[140:143], v[62:63], off
	global_load_dwordx4 v[144:147], v[118:119], off
	v_add_co_u32_e32 v62, vcc, 0x180000, v58
	s_nop 1
	v_addc_co_u32_e32 v63, vcc, 0, v59, vcc
	v_add_co_u32_e32 v58, vcc, 0x1c0000, v58
	global_load_dwordx4 v[148:151], v[62:63], off
	s_nop 0
	v_addc_co_u32_e32 v59, vcc, 0, v59, vcc
	global_load_dwordx4 v[152:155], v[58:59], off
	s_waitcnt vmcnt(7)
	v_pk_fma_f32 v[54:55], v[54:55], s[2:3], v[116:117] op_sel_hi:[1,0,1]
	v_pk_fma_f32 v[52:53], v[52:53], s[2:3], v[114:115] op_sel_hi:[1,0,1]
	s_waitcnt vmcnt(6)
	v_pk_add_f32 v[54:55], v[54:55], v[130:131]
	v_pk_add_f32 v[52:53], v[52:53], v[128:129]
	s_waitcnt vmcnt(5)
	v_pk_add_f32 v[54:55], v[54:55], v[134:135]
	v_pk_add_f32 v[52:53], v[52:53], v[132:133]
	s_waitcnt vmcnt(4)
	v_pk_add_f32 v[54:55], v[54:55], v[138:139]
	v_pk_add_f32 v[52:53], v[52:53], v[136:137]
	s_waitcnt vmcnt(3)
	v_pk_add_f32 v[54:55], v[54:55], v[142:143]
	v_pk_add_f32 v[52:53], v[52:53], v[140:141]
	s_waitcnt vmcnt(2)
	v_pk_add_f32 v[54:55], v[54:55], v[146:147]
	v_pk_add_f32 v[52:53], v[52:53], v[144:145]
	s_waitcnt vmcnt(1)
	v_pk_add_f32 v[54:55], v[54:55], v[150:151]
	v_pk_add_f32 v[52:53], v[52:53], v[148:149]
	s_waitcnt vmcnt(0)
	v_pk_add_f32 v[54:55], v[54:55], v[154:155]
	v_pk_add_f32 v[52:53], v[52:53], v[152:153]

; __device__ __forceinline__ void ln_load_row(const Params& p, const float* src, int which, int r, int lane, f32x4 (&x)[8]) {
;     ...
;     const int wg = gid * 64 + k * gsz + (pm - fm), off = wg % 36, xcd = wg / 36;
;     if (off >= 32) {
;       const int j = (off - 32) * 8 + xcd;
;       f32x4 v = *(const f32x4*)(rs + 256 * k + 4 * lane) * ALPHA;
;       const float* pp = part + (size_t)j * 8 * 65536 + (r & 255) * 256 + 4 * lane;
;       f32x4 t[8];
; #pragma unroll
;       for (int q = 0; q < 8; ++q) t[q] = *(const f32x4*)(pp + (size_t)q * 65536);
; #pragma unroll
;       for (int q = 0; q < 8; ++q) v += t[q];
;       x[k] = v;
.LBB0_1521:
	s_andn2_saveexec_b64 s[36:37], s[36:37]
	s_cbranch_execz .LBB0_1523
	v_lshlrev_b32_e32 v56, 3, v63
	s_movk_i32 s29, 0xff00
	v_add3_u32 v62, v62, v56, s29
	v_ashrrev_i32_e32 v63, 31, v62
	v_add_co_u32_e32 v56, vcc, 0x10a000, v110
	v_lshlrev_b64 v[62:63], 21, v[62:63]
	s_nop 0
	v_addc_co_u32_e32 v57, vcc, 0, v111, vcc
	v_lshl_add_u64 v[62:63], v[112:113], 0, v[62:63]
	v_add_co_u32_e32 v118, vcc, 0x40000, v62
	global_load_dwordx4 v[56:59], v[56:57], off offset:2048
	s_nop 0
	v_addc_co_u32_e32 v119, vcc, 0, v63, vcc
	global_load_dwordx4 v[114:117], v[62:63], off
	global_load_dwordx4 v[128:131], v[118:119], off
	v_add_co_u32_e32 v118, vcc, 0x80000, v62
	s_nop 1
	v_addc_co_u32_e32 v119, vcc, 0, v63, vcc
	v_add_co_u32_e32 v136, vcc, 0xc0000, v62
	s_nop 0
	s_nop 1
	v_addc_co_u32_e32 v137, vcc, 0, v63, vcc
	global_load_dwordx4 v[132:135], v[118:119], off
	s_nop 0
	global_load_dwordx4 v[136:139], v[136:137], off
	v_add_co_u32_e32 v118, vcc, 0x100000, v62
	s_nop 0
	s_nop 1
	v_addc_co_u32_e32 v119, vcc, 0, v63, vcc
	v_add_co_u32_e32 v144, vcc, 0x140000, v62
	s_nop 0
	s_nop 1
	v_addc_co_u32_e32 v145, vcc, 0, v63, vcc
	global_load_dwordx4 v[140:143], v[118:119], off
	s_nop 0
	global_load_dwordx4 v[144:147], v[144:145], off
	v_add_co_u32_e32 v118, vcc, 0x180000, v62
	s_nop 1
	v_addc_co_u32_e32 v119, vcc, 0, v63, vcc
	v_add_co_u32_e32 v62, vcc, 0x1c0000, v62
	global_load_dwordx4 v[148:151], v[118:119], off
	s_nop 0
	v_addc_co_u32_e32 v63, vcc, 0, v63, vcc
	global_load_dwordx4 v[152:155], v[62:63], off
	s_waitcnt vmcnt(7)
	v_pk_fma_f32 v[58:59], v[58:59], s[2:3], v[116:117] op_sel_hi:[1,0,1]
	v_pk_fma_f32 v[56:57], v[56:57], s[2:3], v[114:115] op_sel_hi:[1,0,1]
	s_waitcnt vmcnt(6)
	v_pk_add_f32 v[58:59], v[58:59], v[130:131]
	v_pk_add_f32 v[56:57], v[56:57], v[128:129]
	s_waitcnt vmcnt(5)
	v_pk_add_f32 v[58:59], v[58:59], v[134:135]
	v_pk_add_f32 v[56:57], v[56:57], v[132:133]
	s_waitcnt vmcnt(4)
	v_pk_add_f32 v[58:59], v[58:59], v[138:139]
	v_pk_add_f32 v[56:57], v[56:57], v[136:137]
	s_waitcnt vmcnt(3)
	v_pk_add_f32 v[58:59], v[58:59], v[142:143]
	v_pk_add_f32 v[56:57], v[56:57], v[140:141]
	s_waitcnt vmcnt(2)
	v_pk_add_f32 v[58:59], v[58:59], v[146:147]
	v_pk_add_f32 v[56:57], v[56:57], v[144:145]
	s_waitcnt vmcnt(1)
	v_pk_add_f32 v[58:59], v[58:59], v[150:151]
	v_pk_add_f32 v[56:57], v[56:57], v[148:149]
	s_waitcnt vmcnt(0)
	v_pk_add_f32 v[58:59], v[58:59], v[154:155]
	v_pk_add_f32 v[56:57], v[56:57], v[152:153]

; __device__ __forceinline__ void ln_load_row(const Params& p, const float* src, int which, int r, int lane, f32x4 (&x)[8]) {
;     ...
;     const int wg = gid * 64 + k * gsz + (pm - fm), off = wg % 36, xcd = wg / 36;
;     if (off >= 32) {
;       const int j = (off - 32) * 8 + xcd;
;       f32x4 v = *(const f32x4*)(rs + 256 * k + 4 * lane) * ALPHA;
;       const float* pp = part + (size_t)j * 8 * 65536 + (r & 255) * 256 + 4 * lane;
;       f32x4 t[8];
; #pragma unroll
;       for (int q = 0; q < 8; ++q) t[q] = *(const f32x4*)(pp + (size_t)q * 65536);
; #pragma unroll
;       for (int q = 0; q < 8; ++q) v += t[q];
;       x[k] = v;
.LBB0_1525:
	s_andn2_saveexec_b64 s[36:37], s[36:37]
	s_cbranch_execz .LBB0_1527
	v_lshlrev_b32_e32 v60, 3, v67
	s_movk_i32 s29, 0xff00
	v_add3_u32 v114, v64, v60, s29
	v_add_co_u32_e32 v60, vcc, 0x10a000, v110
	v_ashrrev_i32_e32 v115, 31, v114
	s_nop 0
	v_addc_co_u32_e32 v61, vcc, 0, v111, vcc
	v_lshlrev_b64 v[110:111], 21, v[114:115]
	v_lshl_add_u64 v[118:119], v[112:113], 0, v[110:111]
	v_add_co_u32_e32 v114, vcc, 0x40000, v118
	global_load_dwordx4 v[60:63], v[60:61], off offset:3072
	s_nop 0
	v_addc_co_u32_e32 v115, vcc, 0, v119, vcc
	v_add_co_u32_e32 v128, vcc, 0x80000, v118
	global_load_dwordx4 v[110:113], v[118:119], off
	s_nop 0
	global_load_dwordx4 v[114:117], v[114:115], off
	v_addc_co_u32_e32 v129, vcc, 0, v119, vcc
	v_add_co_u32_e32 v132, vcc, 0xc0000, v118
	s_nop 1
	v_addc_co_u32_e32 v133, vcc, 0, v119, vcc
	v_add_co_u32_e32 v136, vcc, 0x100000, v118
	global_load_dwordx4 v[128:131], v[128:129], off
	s_nop 0
	global_load_dwordx4 v[132:135], v[132:133], off
	v_addc_co_u32_e32 v137, vcc, 0, v119, vcc
	v_add_co_u32_e32 v140, vcc, 0x140000, v118
	s_nop 0
	s_nop 1
	v_addc_co_u32_e32 v141, vcc, 0, v119, vcc
	v_add_co_u32_e32 v144, vcc, 0x180000, v118
	global_load_dwordx4 v[136:139], v[136:137], off
	s_nop 0
	global_load_dwordx4 v[140:143], v[140:141], off
	v_addc_co_u32_e32 v145, vcc, 0, v119, vcc
	v_add_co_u32_e32 v118, vcc, 0x1c0000, v118
	global_load_dwordx4 v[144:147], v[144:145], off
	s_nop 0
	v_addc_co_u32_e32 v119, vcc, 0, v119, vcc
	global_load_dwordx4 v[148:151], v[118:119], off
	s_waitcnt vmcnt(7)
	v_pk_fma_f32 v[62:63], v[62:63], s[2:3], v[112:113] op_sel_hi:[1,0,1]
	v_pk_fma_f32 v[60:61], v[60:61], s[2:3], v[110:111] op_sel_hi:[1,0,1]
	s_waitcnt vmcnt(6)
	v_pk_add_f32 v[62:63], v[62:63], v[116:117]
	v_pk_add_f32 v[60:61], v[60:61], v[114:115]
	s_waitcnt vmcnt(5)
	v_pk_add_f32 v[62:63], v[62:63], v[130:131]
	v_pk_add_f32 v[60:61], v[60:61], v[128:129]
	s_waitcnt vmcnt(4)
	v_pk_add_f32 v[62:63], v[62:63], v[134:135]
	v_pk_add_f32 v[60:61], v[60:61], v[132:133]
	s_waitcnt vmcnt(3)
	v_pk_add_f32 v[62:63], v[62:63], v[138:139]
	v_pk_add_f32 v[60:61], v[60:61], v[136:137]
	s_waitcnt vmcnt(2)
	v_pk_add_f32 v[62:63], v[62:63], v[142:143]
	v_pk_add_f32 v[60:61], v[60:61], v[140:141]
	s_waitcnt vmcnt(1)
	v_pk_add_f32 v[62:63], v[62:63], v[146:147]
	v_pk_add_f32 v[60:61], v[60:61], v[144:145]
	s_waitcnt vmcnt(0)
	v_pk_add_f32 v[62:63], v[62:63], v[150:151]
	v_pk_add_f32 v[60:61], v[60:61], v[148:149]

; __device__ __forceinline__ void ln_load_row(const Params& p, const float* src, int which, int r, int lane, f32x4 (&x)[8]) {
;     ...
;     const int wg = gid * 64 + k * gsz + (pm - fm), off = wg % 36, xcd = wg / 36;
;     if (off >= 32) {
;       const int j = (off - 32) * 8 + xcd;
;       f32x4 v = *(const f32x4*)(rs + 256 * k + 4 * lane) * ALPHA;
;       const float* pp = part + (size_t)j * 8 * 65536 + (r & 255) * 256 + 4 * lane;
;       f32x4 t[8];
; #pragma unroll
;       for (int q = 0; q < 8; ++q) t[q] = *(const f32x4*)(pp + (size_t)q * 65536);
; #pragma unroll
;       for (int q = 0; q < 8; ++q) v += t[q];
;       x[k] = v;
.LBB0_1530:
	s_or_saveexec_b64 s[44:45], s[44:45]
	v_readlane_b32 s29, v255, 10
	v_lshl_add_u64 v[114:115], v[90:91], 0, v[4:5]
	s_nop 0
	v_add_u32_e32 v4, s29, v126
	v_and_b32_e32 v4, 0xff00, v4
	v_lshlrev_b32_e32 v64, 2, v4
	v_lshl_add_u64 v[116:117], v[92:93], 0, v[64:65]
	s_xor_b64 exec, exec, s[44:45]
	s_cbranch_execz .LBB0_1532
	v_lshlrev_b32_e32 v0, 3, v9
	s_movk_i32 s29, 0xff00
	v_add3_u32 v4, v8, v0, s29
	v_ashrrev_i32_e32 v5, 31, v4
	v_lshlrev_b64 v[4:5], 21, v[4:5]
	v_lshl_add_u64 v[4:5], v[116:117], 0, v[4:5]
	v_add_co_u32_e32 v12, vcc, 0x40000, v4
	global_load_dwordx4 v[0:3], v[114:115], off
	s_nop 0
	v_addc_co_u32_e32 v13, vcc, 0, v5, vcc
	v_add_co_u32_e32 v16, vcc, 0x80000, v4
	global_load_dwordx4 v[8:11], v[4:5], off
	s_nop 0
	global_load_dwordx4 v[12:15], v[12:13], off
	v_addc_co_u32_e32 v17, vcc, 0, v5, vcc
	v_add_co_u32_e32 v24, vcc, 0xc0000, v4
	s_nop 1
	v_addc_co_u32_e32 v25, vcc, 0, v5, vcc
	v_add_co_u32_e32 v32, vcc, 0x100000, v4
	global_load_dwordx4 v[16:19], v[16:17], off
	s_nop 0
	global_load_dwordx4 v[24:27], v[24:25], off
	v_addc_co_u32_e32 v33, vcc, 0, v5, vcc
	v_add_co_u32_e32 v40, vcc, 0x140000, v4
	s_nop 0
	s_nop 1
	v_addc_co_u32_e32 v41, vcc, 0, v5, vcc
	v_add_co_u32_e32 v118, vcc, 0x180000, v4
	global_load_dwordx4 v[32:35], v[32:33], off
	s_nop 0
	global_load_dwordx4 v[40:43], v[40:41], off
	v_addc_co_u32_e32 v119, vcc, 0, v5, vcc
	v_add_co_u32_e32 v4, vcc, 0x1c0000, v4
	global_load_dwordx4 v[128:131], v[118:119], off
	s_nop 0
	v_addc_co_u32_e32 v5, vcc, 0, v5, vcc
	global_load_dwordx4 v[132:135], v[4:5], off
	s_waitcnt vmcnt(7)
	v_pk_fma_f32 v[2:3], v[2:3], s[2:3], v[10:11] op_sel_hi:[1,0,1]
	v_pk_fma_f32 v[0:1], v[0:1], s[2:3], v[8:9] op_sel_hi:[1,0,1]
	s_waitcnt vmcnt(6)
	v_pk_add_f32 v[2:3], v[2:3], v[14:15]
	v_pk_add_f32 v[0:1], v[0:1], v[12:13]
	s_waitcnt vmcnt(5)
	v_pk_add_f32 v[2:3], v[2:3], v[18:19]
	v_pk_add_f32 v[0:1], v[0:1], v[16:17]
	s_waitcnt vmcnt(4)
	v_pk_add_f32 v[2:3], v[2:3], v[26:27]
	v_pk_add_f32 v[0:1], v[0:1], v[24:25]
	s_waitcnt vmcnt(3)
	v_pk_add_f32 v[2:3], v[2:3], v[34:35]
	v_pk_add_f32 v[0:1], v[0:1], v[32:33]
	s_waitcnt vmcnt(2)
	v_pk_add_f32 v[2:3], v[2:3], v[42:43]
	v_pk_add_f32 v[0:1], v[0:1], v[40:41]
	s_waitcnt vmcnt(1)
	v_pk_add_f32 v[2:3], v[2:3], v[130:131]
	v_pk_add_f32 v[0:1], v[0:1], v[128:129]
	s_waitcnt vmcnt(0)
	v_pk_add_f32 v[2:3], v[2:3], v[134:135]
	v_pk_add_f32 v[0:1], v[0:1], v[132:133]

; __device__ __forceinline__ void ln_load_row(const Params& p, const float* src, int which, int r, int lane, f32x4 (&x)[8]) {
;     ...
;     const int wg = gid * 64 + k * gsz + (pm - fm), off = wg % 36, xcd = wg / 36;
;     if (off >= 32) {
;       const int j = (off - 32) * 8 + xcd;
;       f32x4 v = *(const f32x4*)(rs + 256 * k + 4 * lane) * ALPHA;
;       const float* pp = part + (size_t)j * 8 * 65536 + (r & 255) * 256 + 4 * lane;
;       f32x4 t[8];
; #pragma unroll
;       for (int q = 0; q < 8; ++q) t[q] = *(const f32x4*)(pp + (size_t)q * 65536);
; #pragma unroll
;       for (int q = 0; q < 8; ++q) v += t[q];
;       x[k] = v;
.LBB0_1534:
	s_andn2_saveexec_b64 s[44:45], s[44:45]
	s_cbranch_execz .LBB0_1536
	v_lshlrev_b32_e32 v4, 3, v10
	s_movk_i32 s29, 0xff00
	v_add3_u32 v10, v9, v4, s29
	v_ashrrev_i32_e32 v11, 31, v10
	v_lshlrev_b64 v[10:11], 21, v[10:11]
	v_lshl_add_u64 v[18:19], v[116:117], 0, v[10:11]
	v_add_co_u32_e32 v14, vcc, 0x40000, v18
	global_load_dwordx4 v[4:7], v[114:115], off offset:1024
	s_nop 0
	v_addc_co_u32_e32 v15, vcc, 0, v19, vcc
	v_add_co_u32_e32 v24, vcc, 0x80000, v18
	global_load_dwordx4 v[10:13], v[18:19], off
	s_nop 0
	global_load_dwordx4 v[14:17], v[14:15], off
	v_addc_co_u32_e32 v25, vcc, 0, v19, vcc
	v_add_co_u32_e32 v32, vcc, 0xc0000, v18
	s_nop 1
	v_addc_co_u32_e32 v33, vcc, 0, v19, vcc
	v_add_co_u32_e32 v42, vcc, 0x100000, v18
	global_load_dwordx4 v[24:27], v[24:25], off
	s_nop 0
	global_load_dwordx4 v[32:35], v[32:33], off
	v_addc_co_u32_e32 v43, vcc, 0, v19, vcc
	v_add_co_u32_e32 v118, vcc, 0x140000, v18
	s_nop 0
	s_nop 1
	v_addc_co_u32_e32 v119, vcc, 0, v19, vcc
	global_load_dwordx4 v[128:131], v[42:43], off
	global_load_dwordx4 v[132:135], v[118:119], off
	v_add_co_u32_e32 v42, vcc, 0x180000, v18
	s_nop 0
	s_nop 1
	v_addc_co_u32_e32 v43, vcc, 0, v19, vcc
	v_add_co_u32_e32 v18, vcc, 0x1c0000, v18
	global_load_dwordx4 v[136:139], v[42:43], off
	s_nop 0
	v_addc_co_u32_e32 v19, vcc, 0, v19, vcc
	global_load_dwordx4 v[140:143], v[18:19], off
	s_waitcnt vmcnt(7)
	v_pk_fma_f32 v[6:7], v[6:7], s[2:3], v[12:13] op_sel_hi:[1,0,1]
	v_pk_fma_f32 v[4:5], v[4:5], s[2:3], v[10:11] op_sel_hi:[1,0,1]
	s_waitcnt vmcnt(6)
	v_pk_add_f32 v[6:7], v[6:7], v[16:17]
	v_pk_add_f32 v[4:5], v[4:5], v[14:15]
	s_waitcnt vmcnt(5)
	v_pk_add_f32 v[6:7], v[6:7], v[26:27]
	v_pk_add_f32 v[4:5], v[4:5], v[24:25]
	s_waitcnt vmcnt(4)
	v_pk_add_f32 v[6:7], v[6:7], v[34:35]
	v_pk_add_f32 v[4:5], v[4:5], v[32:33]
	s_waitcnt vmcnt(3)
	v_pk_add_f32 v[6:7], v[6:7], v[130:131]
	v_pk_add_f32 v[4:5], v[4:5], v[128:129]
	s_waitcnt vmcnt(2)
	v_pk_add_f32 v[6:7], v[6:7], v[134:135]
	v_pk_add_f32 v[4:5], v[4:5], v[132:133]
	s_waitcnt vmcnt(1)
	v_pk_add_f32 v[6:7], v[6:7], v[138:139]
	v_pk_add_f32 v[4:5], v[4:5], v[136:137]
	s_waitcnt vmcnt(0)
	v_pk_add_f32 v[6:7], v[6:7], v[142:143]
	v_pk_add_f32 v[4:5], v[4:5], v[140:141]

; __device__ __forceinline__ void ln_load_row(const Params& p, const float* src, int which, int r, int lane, f32x4 (&x)[8]) {
;     ...
;     const int wg = gid * 64 + k * gsz + (pm - fm), off = wg % 36, xcd = wg / 36;
;     if (off >= 32) {
;       const int j = (off - 32) * 8 + xcd;
;       f32x4 v = *(const f32x4*)(rs + 256 * k + 4 * lane) * ALPHA;
;       const float* pp = part + (size_t)j * 8 * 65536 + (r & 255) * 256 + 4 * lane;
;       f32x4 t[8];
; #pragma unroll
;       for (int q = 0; q < 8; ++q) t[q] = *(const f32x4*)(pp + (size_t)q * 65536);
; #pragma unroll
;       for (int q = 0; q < 8; ++q) v += t[q];
;       x[k] = v;
.LBB0_1538:
	s_andn2_saveexec_b64 s[44:45], s[44:45]
	s_cbranch_execz .LBB0_1540
	v_lshlrev_b32_e32 v8, 3, v14
	s_movk_i32 s29, 0xff00
	v_add3_u32 v14, v13, v8, s29
	v_ashrrev_i32_e32 v15, 31, v14
	v_lshlrev_b64 v[14:15], 21, v[14:15]
	v_lshl_add_u64 v[18:19], v[116:117], 0, v[14:15]
	v_add_co_u32_e32 v24, vcc, 0x40000, v18
	global_load_dwordx4 v[8:11], v[114:115], off offset:2048
	s_nop 0
	v_addc_co_u32_e32 v25, vcc, 0, v19, vcc
	v_add_co_u32_e32 v32, vcc, 0x80000, v18
	global_load_dwordx4 v[14:17], v[18:19], off
	s_nop 0
	global_load_dwordx4 v[24:27], v[24:25], off
	v_addc_co_u32_e32 v33, vcc, 0, v19, vcc
	v_add_co_u32_e32 v42, vcc, 0xc0000, v18
	s_nop 1
	v_addc_co_u32_e32 v43, vcc, 0, v19, vcc
	global_load_dwordx4 v[32:35], v[32:33], off
	s_nop 0
	global_load_dwordx4 v[128:131], v[42:43], off
	v_add_co_u32_e32 v42, vcc, 0x100000, v18
	s_nop 0
	s_nop 1
	v_addc_co_u32_e32 v43, vcc, 0, v19, vcc
	v_add_co_u32_e32 v118, vcc, 0x140000, v18
	s_nop 0
	s_nop 1
	v_addc_co_u32_e32 v119, vcc, 0, v19, vcc
	global_load_dwordx4 v[132:135], v[42:43], off
	global_load_dwordx4 v[136:139], v[118:119], off
	v_add_co_u32_e32 v42, vcc, 0x180000, v18
	s_nop 0
	s_nop 1
	v_addc_co_u32_e32 v43, vcc, 0, v19, vcc
	v_add_co_u32_e32 v18, vcc, 0x1c0000, v18
	global_load_dwordx4 v[140:143], v[42:43], off
	s_nop 0
	v_addc_co_u32_e32 v19, vcc, 0, v19, vcc
	global_load_dwordx4 v[144:147], v[18:19], off
	s_waitcnt vmcnt(7)
	v_pk_fma_f32 v[10:11], v[10:11], s[2:3], v[16:17] op_sel_hi:[1,0,1]
	v_pk_fma_f32 v[8:9], v[8:9], s[2:3], v[14:15] op_sel_hi:[1,0,1]
	s_waitcnt vmcnt(6)
	v_pk_add_f32 v[10:11], v[10:11], v[26:27]
	v_pk_add_f32 v[8:9], v[8:9], v[24:25]
	s_waitcnt vmcnt(5)
	v_pk_add_f32 v[10:11], v[10:11], v[34:35]
	v_pk_add_f32 v[8:9], v[8:9], v[32:33]
	s_waitcnt vmcnt(4)
	v_pk_add_f32 v[10:11], v[10:11], v[130:131]
	v_pk_add_f32 v[8:9], v[8:9], v[128:129]
	s_waitcnt vmcnt(3)
	v_pk_add_f32 v[10:11], v[10:11], v[134:135]
	v_pk_add_f32 v[8:9], v[8:9], v[132:133]
	s_waitcnt vmcnt(2)
	v_pk_add_f32 v[10:11], v[10:11], v[138:139]
	v_pk_add_f32 v[8:9], v[8:9], v[136:137]
	s_waitcnt vmcnt(1)
	v_pk_add_f32 v[10:11], v[10:11], v[142:143]
	v_pk_add_f32 v[8:9], v[8:9], v[140:141]
	s_waitcnt vmcnt(0)
	v_pk_add_f32 v[10:11], v[10:11], v[146:147]
	v_pk_add_f32 v[8:9], v[8:9], v[144:145]

; __device__ __forceinline__ void ln_load_row(const Params& p, const float* src, int which, int r, int lane, f32x4 (&x)[8]) {
;     ...
;     const int wg = gid * 64 + k * gsz + (pm - fm), off = wg % 36, xcd = wg / 36;
;     if (off >= 32) {
;       const int j = (off - 32) * 8 + xcd;
;       f32x4 v = *(const f32x4*)(rs + 256 * k + 4 * lane) * ALPHA;
;       const float* pp = part + (size_t)j * 8 * 65536 + (r & 255) * 256 + 4 * lane;
;       f32x4 t[8];
; #pragma unroll
;       for (int q = 0; q < 8; ++q) t[q] = *(const f32x4*)(pp + (size_t)q * 65536);
; #pragma unroll
;       for (int q = 0; q < 8; ++q) v += t[q];
;       x[k] = v;
.LBB0_1542:
	s_andn2_saveexec_b64 s[44:45], s[44:45]
	s_cbranch_execz .LBB0_1544
	v_lshlrev_b32_e32 v12, 3, v18
	s_movk_i32 s29, 0xff00
	v_add3_u32 v18, v17, v12, s29
	v_ashrrev_i32_e32 v19, 31, v18
	v_lshlrev_b64 v[18:19], 21, v[18:19]
	v_lshl_add_u64 v[18:19], v[116:117], 0, v[18:19]
	v_add_co_u32_e32 v32, vcc, 0x40000, v18
	global_load_dwordx4 v[12:15], v[114:115], off offset:3072
	s_nop 0
	v_addc_co_u32_e32 v33, vcc, 0, v19, vcc
	v_add_co_u32_e32 v42, vcc, 0x80000, v18
	global_load_dwordx4 v[24:27], v[18:19], off
	s_nop 0
	global_load_dwordx4 v[32:35], v[32:33], off
	v_addc_co_u32_e32 v43, vcc, 0, v19, vcc
	v_add_co_u32_e32 v118, vcc, 0xc0000, v18
	s_nop 1
	v_addc_co_u32_e32 v119, vcc, 0, v19, vcc
	global_load_dwordx4 v[128:131], v[42:43], off
	global_load_dwordx4 v[132:135], v[118:119], off
	v_add_co_u32_e32 v42, vcc, 0x100000, v18
	s_nop 0
	s_nop 1
	v_addc_co_u32_e32 v43, vcc, 0, v19, vcc
	v_add_co_u32_e32 v118, vcc, 0x140000, v18
	s_nop 0
	s_nop 1
	v_addc_co_u32_e32 v119, vcc, 0, v19, vcc
	global_load_dwordx4 v[136:139], v[42:43], off
	global_load_dwordx4 v[140:143], v[118:119], off
	v_add_co_u32_e32 v42, vcc, 0x180000, v18
	s_nop 0
	s_nop 1
	v_addc_co_u32_e32 v43, vcc, 0, v19, vcc
	v_add_co_u32_e32 v18, vcc, 0x1c0000, v18
	global_load_dwordx4 v[144:147], v[42:43], off
	s_nop 0
	v_addc_co_u32_e32 v19, vcc, 0, v19, vcc
	global_load_dwordx4 v[148:151], v[18:19], off
	s_waitcnt vmcnt(7)
	v_pk_fma_f32 v[14:15], v[14:15], s[2:3], v[26:27] op_sel_hi:[1,0,1]
	v_pk_fma_f32 v[12:13], v[12:13], s[2:3], v[24:25] op_sel_hi:[1,0,1]
	s_waitcnt vmcnt(6)
	v_pk_add_f32 v[14:15], v[14:15], v[34:35]
	v_pk_add_f32 v[12:13], v[12:13], v[32:33]
	s_waitcnt vmcnt(5)
	v_pk_add_f32 v[14:15], v[14:15], v[130:131]
	v_pk_add_f32 v[12:13], v[12:13], v[128:129]
	s_waitcnt vmcnt(4)
	v_pk_add_f32 v[14:15], v[14:15], v[134:135]
	v_pk_add_f32 v[12:13], v[12:13], v[132:133]
	s_waitcnt vmcnt(3)
	v_pk_add_f32 v[14:15], v[14:15], v[138:139]
	v_pk_add_f32 v[12:13], v[12:13], v[136:137]
	s_waitcnt vmcnt(2)
	v_pk_add_f32 v[14:15], v[14:15], v[142:143]
	v_pk_add_f32 v[12:13], v[12:13], v[140:141]
	s_waitcnt vmcnt(1)
	v_pk_add_f32 v[14:15], v[14:15], v[146:147]
	v_pk_add_f32 v[12:13], v[12:13], v[144:145]
	s_waitcnt vmcnt(0)
	v_pk_add_f32 v[14:15], v[14:15], v[150:151]
	v_pk_add_f32 v[12:13], v[12:13], v[148:149]

; __device__ __forceinline__ void ln_load_row(const Params& p, const float* src, int which, int r, int lane, f32x4 (&x)[8]) {
;     ...
;     const int wg = gid * 64 + k * gsz + (pm - fm), off = wg % 36, xcd = wg / 36;
;     if (off >= 32) {
;       const int j = (off - 32) * 8 + xcd;
;       f32x4 v = *(const f32x4*)(rs + 256 * k + 4 * lane) * ALPHA;
;       const float* pp = part + (size_t)j * 8 * 65536 + (r & 255) * 256 + 4 * lane;
;       f32x4 t[8];
; #pragma unroll
;       for (int q = 0; q < 8; ++q) t[q] = *(const f32x4*)(pp + (size_t)q * 65536);
; #pragma unroll
;       for (int q = 0; q < 8; ++q) v += t[q];
;       x[k] = v;
.LBB0_1546:
	s_andn2_saveexec_b64 s[44:45], s[44:45]
	s_cbranch_execz .LBB0_1548
	v_lshlrev_b32_e32 v16, 3, v26
	s_movk_i32 s29, 0xff00
	v_add3_u32 v16, v25, v16, s29
	v_ashrrev_i32_e32 v17, 31, v16
	v_add_co_u32_e32 v18, vcc, 0x1000, v114
	v_lshlrev_b64 v[16:17], 21, v[16:17]
	s_nop 0
	v_addc_co_u32_e32 v19, vcc, 0, v115, vcc
	v_lshl_add_u64 v[26:27], v[116:117], 0, v[16:17]
	v_add_co_u32_e32 v42, vcc, 0x40000, v26
	global_load_dwordx4 v[16:19], v[18:19], off
	s_nop 0
	global_load_dwordx4 v[32:35], v[26:27], off
	v_addc_co_u32_e32 v43, vcc, 0, v27, vcc
	v_add_co_u32_e32 v118, vcc, 0x80000, v26
	s_nop 1
	v_addc_co_u32_e32 v119, vcc, 0, v27, vcc
	global_load_dwordx4 v[128:131], v[42:43], off
	global_load_dwordx4 v[132:135], v[118:119], off
	v_add_co_u32_e32 v42, vcc, 0xc0000, v26
	s_nop 0
	s_nop 1
	v_addc_co_u32_e32 v43, vcc, 0, v27, vcc
	v_add_co_u32_e32 v118, vcc, 0x100000, v26
	s_nop 1
	v_addc_co_u32_e32 v119, vcc, 0, v27, vcc
	global_load_dwordx4 v[136:139], v[42:43], off
	global_load_dwordx4 v[140:143], v[118:119], off
	v_add_co_u32_e32 v42, vcc, 0x140000, v26
	s_nop 0
	s_nop 1
	v_addc_co_u32_e32 v43, vcc, 0, v27, vcc
	v_add_co_u32_e32 v118, vcc, 0x180000, v26
	s_nop 0
	s_nop 1
	v_addc_co_u32_e32 v119, vcc, 0, v27, vcc
	v_add_co_u32_e32 v26, vcc, 0x1c0000, v26
	global_load_dwordx4 v[144:147], v[42:43], off
	global_load_dwordx4 v[148:151], v[118:119], off
	v_addc_co_u32_e32 v27, vcc, 0, v27, vcc
	global_load_dwordx4 v[152:155], v[26:27], off
	s_waitcnt vmcnt(7)
	v_pk_fma_f32 v[18:19], v[18:19], s[2:3], v[34:35] op_sel_hi:[1,0,1]
	v_pk_fma_f32 v[16:17], v[16:17], s[2:3], v[32:33] op_sel_hi:[1,0,1]
	s_waitcnt vmcnt(6)
	v_pk_add_f32 v[18:19], v[18:19], v[130:131]
	v_pk_add_f32 v[16:17], v[16:17], v[128:129]
	s_waitcnt vmcnt(5)
	v_pk_add_f32 v[18:19], v[18:19], v[134:135]
	v_pk_add_f32 v[16:17], v[16:17], v[132:133]
	s_waitcnt vmcnt(4)
	v_pk_add_f32 v[18:19], v[18:19], v[138:139]
	v_pk_add_f32 v[16:17], v[16:17], v[136:137]
	s_waitcnt vmcnt(3)
	v_pk_add_f32 v[18:19], v[18:19], v[142:143]
	v_pk_add_f32 v[16:17], v[16:17], v[140:141]
	s_waitcnt vmcnt(2)
	v_pk_add_f32 v[18:19], v[18:19], v[146:147]
	v_pk_add_f32 v[16:17], v[16:17], v[144:145]
	s_waitcnt vmcnt(1)
	v_pk_add_f32 v[18:19], v[18:19], v[150:151]
	v_pk_add_f32 v[16:17], v[16:17], v[148:149]
	s_waitcnt vmcnt(0)
	v_pk_add_f32 v[18:19], v[18:19], v[154:155]
	v_pk_add_f32 v[16:17], v[16:17], v[152:153]

; __device__ __forceinline__ void ln_load_row(const Params& p, const float* src, int which, int r, int lane, f32x4 (&x)[8]) {
;     ...
;     const int wg = gid * 64 + k * gsz + (pm - fm), off = wg % 36, xcd = wg / 36;
;     if (off >= 32) {
;       const int j = (off - 32) * 8 + xcd;
;       f32x4 v = *(const f32x4*)(rs + 256 * k + 4 * lane) * ALPHA;
;       const float* pp = part + (size_t)j * 8 * 65536 + (r & 255) * 256 + 4 * lane;
;       f32x4 t[8];
; #pragma unroll
;       for (int q = 0; q < 8; ++q) t[q] = *(const f32x4*)(pp + (size_t)q * 65536);
; #pragma unroll
;       for (int q = 0; q < 8; ++q) v += t[q];
;       x[k] = v;
.LBB0_1550:
	s_andn2_saveexec_b64 s[44:45], s[44:45]
	s_cbranch_execz .LBB0_1552
	v_lshlrev_b32_e32 v24, 3, v34
	s_movk_i32 s29, 0xff00
	v_add3_u32 v24, v33, v24, s29
	v_ashrrev_i32_e32 v25, 31, v24
	v_add_co_u32_e32 v26, vcc, 0x1000, v114
	v_lshlrev_b64 v[24:25], 21, v[24:25]
	s_nop 0
	v_addc_co_u32_e32 v27, vcc, 0, v115, vcc
	v_lshl_add_u64 v[34:35], v[116:117], 0, v[24:25]
	v_add_co_u32_e32 v42, vcc, 0x40000, v34
	global_load_dwordx4 v[24:27], v[26:27], off offset:1024
	s_nop 0
	global_load_dwordx4 v[128:131], v[34:35], off
	v_addc_co_u32_e32 v43, vcc, 0, v35, vcc
	v_add_co_u32_e32 v118, vcc, 0x80000, v34
	s_nop 1
	v_addc_co_u32_e32 v119, vcc, 0, v35, vcc
	global_load_dwordx4 v[132:135], v[42:43], off
	global_load_dwordx4 v[136:139], v[118:119], off
	v_add_co_u32_e32 v42, vcc, 0xc0000, v34
	s_nop 0
	s_nop 1
	v_addc_co_u32_e32 v43, vcc, 0, v35, vcc
	v_add_co_u32_e32 v118, vcc, 0x100000, v34
	s_nop 1
	v_addc_co_u32_e32 v119, vcc, 0, v35, vcc
	global_load_dwordx4 v[140:143], v[42:43], off
	global_load_dwordx4 v[144:147], v[118:119], off
	v_add_co_u32_e32 v42, vcc, 0x140000, v34
	s_nop 0
	s_nop 1
	v_addc_co_u32_e32 v43, vcc, 0, v35, vcc
	v_add_co_u32_e32 v118, vcc, 0x180000, v34
	s_nop 0
	s_nop 1
	v_addc_co_u32_e32 v119, vcc, 0, v35, vcc
	v_add_co_u32_e32 v34, vcc, 0x1c0000, v34
	global_load_dwordx4 v[148:151], v[42:43], off
	global_load_dwordx4 v[152:155], v[118:119], off
	v_addc_co_u32_e32 v35, vcc, 0, v35, vcc
	global_load_dwordx4 v[156:159], v[34:35], off
	s_waitcnt vmcnt(7)
	v_pk_fma_f32 v[26:27], v[26:27], s[2:3], v[130:131] op_sel_hi:[1,0,1]
	v_pk_fma_f32 v[24:25], v[24:25], s[2:3], v[128:129] op_sel_hi:[1,0,1]
	s_waitcnt vmcnt(6)
	v_pk_add_f32 v[26:27], v[26:27], v[134:135]
	v_pk_add_f32 v[24:25], v[24:25], v[132:133]
	s_waitcnt vmcnt(5)
	v_pk_add_f32 v[26:27], v[26:27], v[138:139]
	v_pk_add_f32 v[24:25], v[24:25], v[136:137]
	s_waitcnt vmcnt(4)
	v_pk_add_f32 v[26:27], v[26:27], v[142:143]
	v_pk_add_f32 v[24:25], v[24:25], v[140:141]
	s_waitcnt vmcnt(3)
	v_pk_add_f32 v[26:27], v[26:27], v[146:147]
	v_pk_add_f32 v[24:25], v[24:25], v[144:145]
	s_waitcnt vmcnt(2)
	v_pk_add_f32 v[26:27], v[26:27], v[150:151]
	v_pk_add_f32 v[24:25], v[24:25], v[148:149]
	s_waitcnt vmcnt(1)
	v_pk_add_f32 v[26:27], v[26:27], v[154:155]
	v_pk_add_f32 v[24:25], v[24:25], v[152:153]
	s_waitcnt vmcnt(0)
	v_pk_add_f32 v[26:27], v[26:27], v[158:159]
	v_pk_add_f32 v[24:25], v[24:25], v[156:157]

; __device__ __forceinline__ void ln_load_row(const Params& p, const float* src, int which, int r, int lane, f32x4 (&x)[8]) {
;     ...
;     const int wg = gid * 64 + k * gsz + (pm - fm), off = wg % 36, xcd = wg / 36;
;     if (off >= 32) {
;       const int j = (off - 32) * 8 + xcd;
;       f32x4 v = *(const f32x4*)(rs + 256 * k + 4 * lane) * ALPHA;
;       const float* pp = part + (size_t)j * 8 * 65536 + (r & 255) * 256 + 4 * lane;
;       f32x4 t[8];
; #pragma unroll
;       for (int q = 0; q < 8; ++q) t[q] = *(const f32x4*)(pp + (size_t)q * 65536);
; #pragma unroll
;       for (int q = 0; q < 8; ++q) v += t[q];
;       x[k] = v;
.LBB0_1554:
	s_andn2_saveexec_b64 s[44:45], s[44:45]
	s_cbranch_execz .LBB0_1556
	v_lshlrev_b32_e32 v32, 3, v43
	s_movk_i32 s29, 0xff00
	v_add3_u32 v32, v42, v32, s29
	v_ashrrev_i32_e32 v33, 31, v32
	v_add_co_u32_e32 v34, vcc, 0x1000, v114
	v_lshlrev_b64 v[32:33], 21, v[32:33]
	s_nop 0
	v_addc_co_u32_e32 v35, vcc, 0, v115, vcc
	v_lshl_add_u64 v[42:43], v[116:117], 0, v[32:33]
	v_add_co_u32_e32 v118, vcc, 0x40000, v42
	global_load_dwordx4 v[32:35], v[34:35], off offset:2048
	s_nop 0
	global_load_dwordx4 v[128:131], v[42:43], off
	v_addc_co_u32_e32 v119, vcc, 0, v43, vcc
	v_add_co_u32_e32 v136, vcc, 0x80000, v42
	s_nop 1
	v_addc_co_u32_e32 v137, vcc, 0, v43, vcc
	global_load_dwordx4 v[132:135], v[118:119], off
	s_nop 0
	global_load_dwordx4 v[136:139], v[136:137], off
	v_add_co_u32_e32 v118, vcc, 0xc0000, v42
	s_nop 0
	s_nop 1
	v_addc_co_u32_e32 v119, vcc, 0, v43, vcc
	v_add_co_u32_e32 v144, vcc, 0x100000, v42
	s_nop 1
	v_addc_co_u32_e32 v145, vcc, 0, v43, vcc
	global_load_dwordx4 v[140:143], v[118:119], off
	s_nop 0
	global_load_dwordx4 v[144:147], v[144:145], off
	v_add_co_u32_e32 v118, vcc, 0x140000, v42
	s_nop 0
	s_nop 1
	v_addc_co_u32_e32 v119, vcc, 0, v43, vcc
	v_add_co_u32_e32 v152, vcc, 0x180000, v42
	s_nop 0
	s_nop 1
	v_addc_co_u32_e32 v153, vcc, 0, v43, vcc
	v_add_co_u32_e32 v42, vcc, 0x1c0000, v42
	global_load_dwordx4 v[148:151], v[118:119], off
	s_nop 0
	global_load_dwordx4 v[152:155], v[152:153], off
	v_addc_co_u32_e32 v43, vcc, 0, v43, vcc
	global_load_dwordx4 v[156:159], v[42:43], off
	s_waitcnt vmcnt(7)
	v_pk_fma_f32 v[34:35], v[34:35], s[2:3], v[130:131] op_sel_hi:[1,0,1]
	v_pk_fma_f32 v[32:33], v[32:33], s[2:3], v[128:129] op_sel_hi:[1,0,1]
	s_waitcnt vmcnt(6)
	v_pk_add_f32 v[34:35], v[34:35], v[134:135]
	v_pk_add_f32 v[32:33], v[32:33], v[132:133]
	s_waitcnt vmcnt(5)
	v_pk_add_f32 v[34:35], v[34:35], v[138:139]
	v_pk_add_f32 v[32:33], v[32:33], v[136:137]
	s_waitcnt vmcnt(4)
	v_pk_add_f32 v[34:35], v[34:35], v[142:143]
	v_pk_add_f32 v[32:33], v[32:33], v[140:141]
	s_waitcnt vmcnt(3)
	v_pk_add_f32 v[34:35], v[34:35], v[146:147]
	v_pk_add_f32 v[32:33], v[32:33], v[144:145]
	s_waitcnt vmcnt(2)
	v_pk_add_f32 v[34:35], v[34:35], v[150:151]
	v_pk_add_f32 v[32:33], v[32:33], v[148:149]
	s_waitcnt vmcnt(1)
	v_pk_add_f32 v[34:35], v[34:35], v[154:155]
	v_pk_add_f32 v[32:33], v[32:33], v[152:153]
	s_waitcnt vmcnt(0)
	v_pk_add_f32 v[34:35], v[34:35], v[158:159]
	v_pk_add_f32 v[32:33], v[32:33], v[156:157]

; __device__ __forceinline__ void ln_load_row(const Params& p, const float* src, int which, int r, int lane, f32x4 (&x)[8]) {
;     ...
;     const int wg = gid * 64 + k * gsz + (pm - fm), off = wg % 36, xcd = wg / 36;
;     if (off >= 32) {
;       const int j = (off - 32) * 8 + xcd;
;       f32x4 v = *(const f32x4*)(rs + 256 * k + 4 * lane) * ALPHA;
;       const float* pp = part + (size_t)j * 8 * 65536 + (r & 255) * 256 + 4 * lane;
;       f32x4 t[8];
; #pragma unroll
;       for (int q = 0; q < 8; ++q) t[q] = *(const f32x4*)(pp + (size_t)q * 65536);
; #pragma unroll
;       for (int q = 0; q < 8; ++q) v += t[q];
;       x[k] = v;
.LBB0_1558:
	s_andn2_saveexec_b64 s[44:45], s[44:45]
	s_cbranch_execz .LBB0_1560
	v_lshlrev_b32_e32 v40, 3, v67
	s_movk_i32 s29, 0xff00
	v_add3_u32 v40, v64, v40, s29
	v_ashrrev_i32_e32 v41, 31, v40
	v_add_co_u32_e32 v42, vcc, 0x1000, v114
	v_lshlrev_b64 v[40:41], 21, v[40:41]
	s_nop 0
	v_addc_co_u32_e32 v43, vcc, 0, v115, vcc
	v_lshl_add_u64 v[148:149], v[116:117], 0, v[40:41]
	v_add_co_u32_e32 v116, vcc, 0x40000, v148
	global_load_dwordx4 v[40:43], v[42:43], off offset:3072
	s_nop 0
	global_load_dwordx4 v[112:115], v[148:149], off
	v_addc_co_u32_e32 v117, vcc, 0, v149, vcc
	v_add_co_u32_e32 v128, vcc, 0x80000, v148
	s_nop 1
	v_addc_co_u32_e32 v129, vcc, 0, v149, vcc
	v_add_co_u32_e32 v132, vcc, 0xc0000, v148
	global_load_dwordx4 v[116:119], v[116:117], off
	s_nop 0
	global_load_dwordx4 v[128:131], v[128:129], off
	v_addc_co_u32_e32 v133, vcc, 0, v149, vcc
	v_add_co_u32_e32 v136, vcc, 0x100000, v148
	s_nop 0
	s_nop 1
	v_addc_co_u32_e32 v137, vcc, 0, v149, vcc
	v_add_co_u32_e32 v140, vcc, 0x140000, v148
	global_load_dwordx4 v[132:135], v[132:133], off
	s_nop 0
	global_load_dwordx4 v[136:139], v[136:137], off
	v_addc_co_u32_e32 v141, vcc, 0, v149, vcc
	v_add_co_u32_e32 v144, vcc, 0x180000, v148
	s_nop 1
	v_addc_co_u32_e32 v145, vcc, 0, v149, vcc
	v_add_co_u32_e32 v148, vcc, 0x1c0000, v148
	global_load_dwordx4 v[140:143], v[140:141], off
	s_nop 0
	global_load_dwordx4 v[144:147], v[144:145], off
	v_addc_co_u32_e32 v149, vcc, 0, v149, vcc
	global_load_dwordx4 v[148:151], v[148:149], off
	s_waitcnt vmcnt(7)
	v_pk_fma_f32 v[42:43], v[42:43], s[2:3], v[114:115] op_sel_hi:[1,0,1]
	v_pk_fma_f32 v[40:41], v[40:41], s[2:3], v[112:113] op_sel_hi:[1,0,1]
	s_waitcnt vmcnt(6)
	v_pk_add_f32 v[42:43], v[42:43], v[118:119]
	v_pk_add_f32 v[40:41], v[40:41], v[116:117]
	s_waitcnt vmcnt(5)
	v_pk_add_f32 v[42:43], v[42:43], v[130:131]
	v_pk_add_f32 v[40:41], v[40:41], v[128:129]
	s_waitcnt vmcnt(4)
	v_pk_add_f32 v[42:43], v[42:43], v[134:135]
	v_pk_add_f32 v[40:41], v[40:41], v[132:133]
	s_waitcnt vmcnt(3)
	v_pk_add_f32 v[42:43], v[42:43], v[138:139]
	v_pk_add_f32 v[40:41], v[40:41], v[136:137]
	s_waitcnt vmcnt(2)
	v_pk_add_f32 v[42:43], v[42:43], v[142:143]
	v_pk_add_f32 v[40:41], v[40:41], v[140:141]
	s_waitcnt vmcnt(1)
	v_pk_add_f32 v[42:43], v[42:43], v[146:147]
	v_pk_add_f32 v[40:41], v[40:41], v[144:145]
	s_waitcnt vmcnt(0)
	v_pk_add_f32 v[42:43], v[42:43], v[150:151]
	v_pk_add_f32 v[40:41], v[40:41], v[148:149]
